# v86 plus J layer-0 loop: next-layer modulation vectors staged in free LDS and read from there
# baseline (speedup 1.0000x reference)
.LBB0_1728:
	s_or_b64 exec, exec, s[10:11]
	v_readlane_b32 s8, v254, 45
	v_readlane_b32 s9, v254, 46
	v_readlane_b32 s22, v254, 32
	v_readlane_b32 s24, v254, 14
	v_readlane_b32 s28, v254, 22
	s_and_b64 vcc, exec, s[8:9]
	v_readlane_b32 s23, v254, 33
	v_readlane_b32 s25, v254, 15
	v_readlane_b32 s29, v254, 23
	v_readlane_b32 s30, v254, 20
	s_waitcnt lgkmcnt(0)
	s_barrier
	v_readlane_b32 s31, v254, 21
	s_add_u32 s84, s46, 0x28e000
	s_addc_u32 s85, s47, 0
	s_add_u32 s86, s46, 0x28c000
	s_addc_u32 s87, s47, 0
	v_lshlrev_b32_e32 v115, 4, v0
	global_load_dwordx4 v[180:183], v115, s[84:85]
	global_load_dwordx4 v[184:187], v115, s[86:87]
	v_add_u32_e32 v117, 0x20400, v115
	s_movk_i32 s90, 0x1c0
	v_cmp_gt_u32_e64 s[88:89], s90, v0
	s_waitcnt vmcnt(0)
	ds_write_b128 v117, v[180:183]
	s_and_saveexec_b64 s[90:91], s[88:89]
	ds_write_b128 v117, v[184:187] offset:8192
	s_mov_b64 exec, s[90:91]
	s_waitcnt lgkmcnt(0)
	s_barrier
	v_lshlrev_b32_e32 v127, 4, v232
	v_add_u32_e32 v127, 0x20400, v127
	s_load_dwordx4 s[76:79], s[0:1], 0xb0
	v_lshlrev_b32_e32 v144, 4, v232
	v_add_u32_e32 v145, 0x1000, v144
	s_waitcnt lgkmcnt(0)
	global_load_dwordx4 v[180:183], v144, s[76:77]
	global_load_dwordx4 v[212:215], v144, s[78:79]
	global_load_dwordx4 v[184:187], v144, s[76:77] offset:1024
	global_load_dwordx4 v[216:219], v144, s[78:79] offset:1024
	global_load_dwordx4 v[188:191], v144, s[76:77] offset:2048
	global_load_dwordx4 v[220:223], v144, s[78:79] offset:2048
	global_load_dwordx4 v[192:195], v144, s[76:77] offset:3072
	global_load_dwordx4 v[236:239], v144, s[78:79] offset:3072
	global_load_dwordx4 v[196:199], v145, s[76:77]
	global_load_dwordx4 v[240:243], v145, s[78:79]
	global_load_dwordx4 v[200:203], v145, s[76:77] offset:1024
	global_load_dwordx4 v[128:131], v145, s[78:79] offset:1024
	global_load_dwordx4 v[204:207], v145, s[76:77] offset:2048
	global_load_dwordx4 v[132:135], v145, s[78:79] offset:2048
	global_load_dwordx4 v[208:211], v145, s[76:77] offset:3072
	global_load_dwordx4 v[140:143], v145, s[78:79] offset:3072
	s_cbranch_vccz .LBB0_1743

.LBB0_1743:
	v_mov_b32_e32 v2, v0
	s_mov_b64 s[8:9], s[44:45]
	v_mov_b32_e32 v1, v232
	s_mov_b64 s[34:35], s[46:47]
	s_mov_b64 s[10:11], s[0:1]
	s_add_i32 s8, s60, s30
	v_lshlrev_b32_e32 v2, 2, v1
	s_waitcnt lgkmcnt(0)
	v_ashrrev_i32_e32 v3, 31, v2
	v_lshlrev_b64 v[4:5], 1, v[2:3]
	v_lshl_add_u64 v[6:7], s[34:35], 0, v[4:5]
	v_lshl_add_u64 v[32:33], v[6:7], 0, s[24:25]
	global_load_dwordx2 v[6:7], v[32:33], off offset:-3584
	global_load_dwordx2 v[34:35], v[32:33], off offset:-3072
	global_load_dwordx2 v[44:45], v[32:33], off offset:-2560
	global_load_dwordx2 v[8:9], v[32:33], off offset:-2048
	s_cmpk_lt_i32 s8, 0x2000
	s_cselect_b32 s36, s8, s30
	s_add_u32 s18, s34, 0x28c000
	s_addc_u32 s19, s35, 0
	s_ashr_i32 s37, s36, 31
	s_ashr_i32 s31, s30, 31
	s_lshl_b64 s[8:9], s[36:37], 12
	s_add_u32 s16, s34, s8
	s_addc_u32 s17, s35, s9
	v_lshl_add_u64 v[4:5], s[16:17], 0, v[4:5]
	s_mov_b64 s[8:9], 0x1d91e000
	v_lshl_add_u64 v[224:225], v[4:5], 0, s[8:9]
	global_load_dwordx2 v[118:119], v[224:225], off
	global_load_dwordx2 v[120:121], v[224:225], off offset:512
	global_load_dwordx2 v[122:123], v[224:225], off offset:1024
	global_load_dwordx2 v[144:145], v[224:225], off offset:1536
	global_load_dwordx2 v[146:147], v[224:225], off offset:2048
	global_load_dwordx2 v[152:153], v[224:225], off offset:2560
	global_load_dwordx2 v[154:155], v[224:225], off offset:3072
	global_load_dwordx2 v[234:235], v[224:225], off offset:3584
	v_and_b32_e32 v14, 64, v249
	v_add_u32_e32 v14, 64, v14
	v_xor_b32_e32 v20, 1, v249
	v_lshlrev_b64 v[86:87], 2, v[2:3]
	s_add_u32 s20, s34, 0x28e000
	s_addc_u32 s21, s35, 0
	v_lshl_add_u64 v[88:89], s[20:21], 0, v[86:87]
	s_add_u32 s58, s34, 0x1515b000
	s_addc_u32 s59, s35, 0
	s_waitcnt vmcnt(3)
	v_lshlrev_b32_e32 v68, 16, v6
	s_waitcnt vmcnt(2)
	v_lshlrev_b32_e32 v69, 16, v34
	v_and_b32_e32 v75, 0xffff0000, v34
	s_waitcnt vmcnt(0)
	v_lshlrev_b32_e32 v36, 16, v8
	v_and_b32_e32 v37, 0xffff0000, v8
	v_lshlrev_b32_e32 v38, 16, v9
	v_and_b32_e32 v39, 0xffff0000, v9
	global_load_dwordx2 v[8:9], v[32:33], off offset:-1536
	v_and_b32_e32 v74, 0xffff0000, v6
	v_and_b32_e32 v73, 0xffff0000, v35
	v_and_b32_e32 v72, 0xffff0000, v7
	v_lshlrev_b32_e32 v34, 16, v44
	v_add_f32_e32 v66, v36, v37
	v_add_f32_e32 v46, v38, v39
	s_waitcnt vmcnt(0)
	v_lshlrev_b32_e32 v43, 16, v8
	v_and_b32_e32 v41, 0xffff0000, v8
	v_lshlrev_b32_e32 v67, 16, v9
	v_and_b32_e32 v47, 0xffff0000, v9
	global_load_dwordx2 v[70:71], v[32:33], off offset:-1024
	global_load_dwordx2 v[8:9], v[32:33], off offset:-512
	s_waitcnt vmcnt(0)
	v_lshlrev_b32_e32 v48, 16, v8
	v_and_b32_e32 v49, 0xffff0000, v8
	v_lshlrev_b32_e32 v50, 16, v9
	v_and_b32_e32 v51, 0xffff0000, v9
	global_load_dwordx2 v[8:9], v[32:33], off
	v_add_f32_e32 v64, v48, v49
	v_add_f32_e32 v54, v50, v51
	s_waitcnt vmcnt(0)
	v_lshlrev_b32_e32 v52, 16, v8
	v_and_b32_e32 v53, 0xffff0000, v8
	v_lshlrev_b32_e32 v65, 16, v9
	v_and_b32_e32 v55, 0xffff0000, v9
	v_lshl_add_u64 v[8:9], v[4:5], 0, s[8:9]
	s_mov_b32 s8, 0x1d91e000
	v_add_co_u32_e32 v4, vcc, s8, v4
	s_nop 1
	v_addc_co_u32_e32 v5, vcc, 0, v5, vcc
	s_nop 1
	v_mov_b64_e32 v[60:61], v[118:119]
	s_nop 1
	v_mov_b64_e32 v[62:63], v[120:121]
	s_nop 1
	v_mov_b64_e32 v[58:59], v[122:123]
	s_nop 0
	s_nop 1
	v_mov_b64_e32 v[4:5], v[144:145]
	v_cmp_lt_i32_e32 vcc, v20, v14
	s_waitcnt vmcnt(0)
	v_lshlrev_b32_e32 v28, 16, v4
	v_and_b32_e32 v29, 0xffff0000, v4
	v_lshlrev_b32_e32 v30, 16, v5
	v_and_b32_e32 v31, 0xffff0000, v5
	s_nop 1
	v_mov_b64_e32 v[4:5], v[146:147]
	v_cndmask_b32_e32 v20, v249, v20, vcc
	v_lshlrev_b32_e32 v90, 2, v20
	v_add_f32_e32 v26, v28, v29
	v_add_f32_e32 v24, v30, v31
	s_waitcnt vmcnt(0)
	v_lshlrev_b32_e32 v23, 16, v4
	v_and_b32_e32 v21, 0xffff0000, v4
	v_lshlrev_b32_e32 v27, 16, v5
	v_and_b32_e32 v25, 0xffff0000, v5
	s_nop 1
	v_mov_b64_e32 v[56:57], v[152:153]
	s_nop 1
	v_mov_b64_e32 v[4:5], v[154:155]
	s_load_dwordx4 s[12:15], s[10:11], 0xb0
	s_load_dwordx2 s[38:39], s[10:11], 0x68
	s_waitcnt lgkmcnt(0)
	v_lshl_add_u64 v[84:85], s[12:13], 0, v[86:87]
	s_waitcnt vmcnt(0)
	v_lshlrev_b32_e32 v16, 16, v4
	v_and_b32_e32 v17, 0xffff0000, v4
	v_lshlrev_b32_e32 v18, 16, v5
	v_and_b32_e32 v19, 0xffff0000, v5
	s_nop 1
	v_mov_b64_e32 v[4:5], v[234:235]
	v_lshlrev_b32_e32 v9, 16, v35
	v_lshlrev_b32_e32 v8, 16, v7
	v_pk_add_f32 v[6:7], v[8:9], v[72:73]
	v_lshlrev_b32_e32 v35, 16, v45
	s_waitcnt vmcnt(0)
	v_lshlrev_b32_e32 v10, 16, v4
	v_and_b32_e32 v11, 0xffff0000, v4
	v_lshlrev_b32_e32 v15, 16, v5
	v_and_b32_e32 v13, 0xffff0000, v5
	v_pk_add_f32 v[4:5], v[68:69], v[74:75]
	s_nop 0
	v_pk_add_f32 v[4:5], v[4:5], v[6:7]
	v_and_b32_e32 v7, 0xffff0000, v45
	v_add_f32_e32 v4, 0, v4
	v_and_b32_e32 v6, 0xffff0000, v44
	v_add_f32_e32 v42, v4, v5
	v_pk_add_f32 v[4:5], v[34:35], v[6:7]
	v_pk_add_f32 v[44:45], v[66:67], v[46:47]
	v_pk_add_f32 v[4:5], v[4:5], v[4:5] op_sel:[0,1] op_sel_hi:[1,0]
	s_nop 0
	v_mov_b32_e32 v5, v41
	v_pk_add_f32 v[4:5], v[42:43], v[4:5]
	s_nop 0
	v_pk_add_f32 v[76:77], v[4:5], v[44:45]
	v_lshlrev_b32_e32 v45, 16, v71
	v_lshlrev_b32_e32 v44, 16, v70
	v_and_b32_e32 v5, 0xffff0000, v71
	v_and_b32_e32 v4, 0xffff0000, v70
	v_pk_add_f32 v[70:71], v[44:45], v[4:5]
	v_pk_add_f32 v[76:77], v[76:77], v[76:77] op_sel:[0,1] op_sel_hi:[1,0]
	v_pk_add_f32 v[70:71], v[70:71], v[70:71] op_sel:[0,1] op_sel_hi:[1,0]
	v_mov_b32_e32 v77, v52
	v_mov_b32_e32 v71, v53
	v_pk_add_f32 v[70:71], v[76:77], v[70:71]
	v_pk_add_f32 v[76:77], v[64:65], v[54:55]
	s_nop 0
	v_pk_add_f32 v[70:71], v[70:71], v[76:77]
	s_nop 0
	v_add_f32_e32 v12, v70, v71
	ds_bpermute_b32 v20, v90, v12
	s_waitcnt lgkmcnt(0)
	v_add_f32_e32 v12, v12, v20
	v_xor_b32_e32 v20, 2, v249
	v_cmp_lt_i32_e32 vcc, v20, v14
	s_nop 1
	v_cndmask_b32_e32 v20, v249, v20, vcc
	v_lshlrev_b32_e32 v91, 2, v20
	ds_bpermute_b32 v20, v91, v12
	s_waitcnt lgkmcnt(0)
	v_add_f32_e32 v12, v12, v20
	v_xor_b32_e32 v20, 4, v249
	v_cmp_lt_i32_e32 vcc, v20, v14
	s_nop 1
	v_cndmask_b32_e32 v20, v249, v20, vcc
	v_lshlrev_b32_e32 v92, 2, v20
	ds_bpermute_b32 v20, v92, v12
	s_waitcnt lgkmcnt(0)
	v_add_f32_e32 v12, v12, v20
	v_xor_b32_e32 v20, 8, v249
	v_cmp_lt_i32_e32 vcc, v20, v14
	s_nop 1
	v_cndmask_b32_e32 v20, v249, v20, vcc
	v_lshlrev_b32_e32 v93, 2, v20
	ds_bpermute_b32 v20, v93, v12
	s_waitcnt lgkmcnt(0)
	v_add_f32_e32 v12, v12, v20
	v_xor_b32_e32 v20, 16, v249
	v_cmp_lt_i32_e32 vcc, v20, v14
	s_nop 1
	v_cndmask_b32_e32 v20, v249, v20, vcc
	v_lshlrev_b32_e32 v94, 2, v20
	ds_bpermute_b32 v20, v94, v12
	s_waitcnt lgkmcnt(0)
	v_add_f32_e32 v12, v12, v20
	v_xor_b32_e32 v20, 32, v249
	v_cmp_lt_i32_e32 vcc, v20, v14
	s_nop 1
	v_cndmask_b32_e32 v14, v249, v20, vcc
	v_lshlrev_b32_e32 v95, 2, v14
	ds_bpermute_b32 v14, v95, v12
	s_waitcnt lgkmcnt(0)
	v_add_f32_e32 v12, v12, v14
	v_fmac_f32_e32 v74, 0xba000000, v12
	v_fmac_f32_e32 v75, 0xba000000, v12
	v_fmac_f32_e32 v72, 0xba000000, v12
	v_fmac_f32_e32 v68, 0xba000000, v12
	v_fmac_f32_e32 v73, 0xba000000, v12
	v_fmac_f32_e32 v69, 0xba000000, v12
	v_mov_b32_e32 v71, v75
	v_mov_b32_e32 v77, v74
	v_pk_mul_f32 v[74:75], v[74:75], v[74:75]
	v_fmac_f32_e32 v8, 0xba000000, v12
	v_fmac_f32_e32 v9, 0xba000000, v12
	v_mov_b32_e32 v70, v69
	v_mov_b32_e32 v76, v68
	v_pk_fma_f32 v[68:69], v[68:69], v[68:69], v[74:75]
	v_mov_b32_e32 v75, v73
	v_mov_b32_e32 v79, v72
	v_pk_mul_f32 v[72:73], v[72:73], v[72:73]
	v_fmac_f32_e32 v6, 0xba000000, v12
	v_fmac_f32_e32 v7, 0xba000000, v12
	v_fmac_f32_e32 v35, 0xba000000, v12
	v_mov_b32_e32 v74, v9
	v_mov_b32_e32 v78, v8
	v_pk_fma_f32 v[8:9], v[8:9], v[8:9], v[72:73]
	v_fmac_f32_e32 v34, 0xba000000, v12
	v_mov_b32_e32 v72, v35
	v_mov_b32_e32 v73, v7
	v_mov_b32_e32 v35, v6
	v_pk_add_f32 v[8:9], v[68:69], v[8:9]
	v_pk_mul_f32 v[68:69], v[72:73], v[72:73]
	v_pk_mul_f32 v[6:7], v[34:35], v[34:35]
	v_fmac_f32_e32 v36, 0xba000000, v12
	v_pk_mov_b32 v[80:81], v[6:7], v[68:69] op_sel:[1,0]
	v_mov_b32_e32 v7, v69
	v_pk_add_f32 v[6:7], v[80:81], v[6:7]
	v_fmac_f32_e32 v37, 0xba000000, v12
	v_pk_add_f32 v[6:7], v[6:7], v[6:7] op_sel_hi:[0,1]
	v_fmac_f32_e32 v38, 0xba000000, v12
	v_mul_f32_e32 v6, v36, v36
	v_fmac_f32_e32 v39, 0xba000000, v12
	v_pk_fma_f32 v[68:69], v[36:37], v[36:37], v[6:7] op_sel_hi:[1,1,0]
	v_mul_f32_e32 v6, v38, v38
	v_pk_add_f32 v[8:9], v[8:9], v[8:9] op_sel_hi:[0,1]
	v_pk_fma_f32 v[80:81], v[38:39], v[38:39], v[6:7] op_sel_hi:[1,1,0]
	v_fmac_f32_e32 v47, 0xba000000, v12
	v_fmac_f32_e32 v67, 0xba000000, v12
	v_fmac_f32_e32 v41, 0xba000000, v12
	v_fmac_f32_e32 v43, 0xba000000, v12
	v_mul_f32_e32 v68, v43, v43
	v_mul_f32_e32 v80, v41, v41
	v_mul_f32_e32 v6, v67, v67
	v_mul_f32_e32 v8, v47, v47
	v_pk_add_f32 v[68:69], v[68:69], v[80:81]
	v_pk_add_f32 v[6:7], v[6:7], v[8:9]
	v_fmac_f32_e32 v4, 0xba000000, v12
	v_fmac_f32_e32 v5, 0xba000000, v12
	v_fmac_f32_e32 v45, 0xba000000, v12
	v_pk_add_f32 v[6:7], v[68:69], v[6:7]
	v_fmac_f32_e32 v44, 0xba000000, v12
	v_mov_b32_e32 v68, v45
	v_mov_b32_e32 v69, v5
	v_mov_b32_e32 v45, v4
	v_pk_mul_f32 v[8:9], v[68:69], v[68:69]
	v_pk_mul_f32 v[4:5], v[44:45], v[44:45]
	v_fmac_f32_e32 v48, 0xba000000, v12
	v_pk_mov_b32 v[80:81], v[4:5], v[8:9] op_sel:[1,0]
	v_mov_b32_e32 v5, v9
	v_pk_add_f32 v[4:5], v[80:81], v[4:5]
	v_fmac_f32_e32 v49, 0xba000000, v12
	v_pk_add_f32 v[4:5], v[4:5], v[4:5] op_sel_hi:[0,1]
	v_fmac_f32_e32 v50, 0xba000000, v12
	v_mul_f32_e32 v4, v48, v48
	v_fmac_f32_e32 v51, 0xba000000, v12
	v_pk_fma_f32 v[8:9], v[48:49], v[48:49], v[4:5] op_sel_hi:[1,1,0]
	v_mul_f32_e32 v4, v50, v50
	v_pk_add_f32 v[6:7], v[6:7], v[6:7] op_sel_hi:[0,1]
	v_pk_fma_f32 v[80:81], v[50:51], v[50:51], v[4:5] op_sel_hi:[1,1,0]
	v_fmac_f32_e32 v55, 0xba000000, v12
	v_fmac_f32_e32 v65, 0xba000000, v12
	v_fmac_f32_e32 v53, 0xba000000, v12
	v_fmac_f32_e32 v52, 0xba000000, v12
	v_mul_f32_e32 v8, v52, v52
	v_mul_f32_e32 v80, v53, v53
	v_mul_f32_e32 v4, v65, v65
	v_mul_f32_e32 v6, v55, v55
	v_pk_add_f32 v[8:9], v[8:9], v[80:81]
	v_pk_add_f32 v[4:5], v[4:5], v[6:7]
	v_lshl_add_u64 v[80:81], s[14:15], 0, v[86:87]
	v_pk_add_f32 v[4:5], v[8:9], v[4:5]
	v_mov_b32_e32 v46, v67
	v_add_f32_e32 v4, v4, v5
	ds_bpermute_b32 v5, v90, v4
	v_mov_b32_e32 v40, v43
	v_mov_b32_e32 v54, v65
	s_waitcnt lgkmcnt(0)
	v_add_f32_e32 v4, v4, v5
	ds_bpermute_b32 v5, v91, v4
	s_waitcnt lgkmcnt(0)
	v_add_f32_e32 v4, v4, v5
	ds_bpermute_b32 v5, v92, v4
	s_waitcnt lgkmcnt(0)
	v_add_f32_e32 v4, v4, v5
	ds_bpermute_b32 v5, v93, v4
	s_waitcnt lgkmcnt(0)
	v_add_f32_e32 v4, v4, v5
	ds_bpermute_b32 v5, v94, v4
	s_waitcnt lgkmcnt(0)
	v_add_f32_e32 v4, v4, v5
	ds_bpermute_b32 v5, v95, v4
	s_waitcnt lgkmcnt(0)
	v_add_f32_e32 v4, v4, v5
	v_fmamk_f32 v4, v4, 0x3a000000, v250
	v_cmp_gt_f32_e32 vcc, s96, v4
	v_mul_f32_e32 v5, 0x4f800000, v4
	s_nop 0
	v_cndmask_b32_e32 v4, v4, v5, vcc
	v_sqrt_f32_e32 v5, v4
	s_nop 0
	v_add_u32_e32 v6, -1, v5
	v_fma_f32 v7, -v6, v5, v4
	v_cmp_ge_f32_e64 s[10:11], 0, v7
	v_add_u32_e32 v7, 1, v5
	s_nop 0
	v_cndmask_b32_e64 v6, v5, v6, s[10:11]
	v_fma_f32 v5, -v7, v5, v4
	v_cmp_lt_f32_e64 s[10:11], 0, v5
	s_nop 1
	v_cndmask_b32_e64 v5, v6, v7, s[10:11]
	v_mul_f32_e32 v6, 0x37800000, v5
	v_cndmask_b32_e32 v5, v5, v6, vcc
	v_cmp_class_f32_e32 vcc, v4, v251
	s_nop 1
	v_cndmask_b32_e32 v4, v5, v4, vcc
	v_div_scale_f32 v5, s[8:9], v4, v4, 1.0
	v_rcp_f32_e32 v6, v5
	s_movk_i32 s8, 0xf000
	v_fma_f32 v7, -v5, v6, 1.0
	v_fmac_f32_e32 v6, v7, v6
	v_div_scale_f32 v7, vcc, 1.0, v4, 1.0
	v_mul_f32_e32 v8, v7, v6
	v_fma_f32 v9, -v5, v8, v7
	v_fmac_f32_e32 v8, v9, v6
	v_fma_f32 v5, -v5, v8, v7
	v_div_fmas_f32 v5, v5, v6, v8
	v_div_fixup_f32 v12, v5, v4, 1.0
	s_nop 1
	v_mov_b64_e32 v[2:3], v[180:181]
	v_mov_b64_e32 v[4:5], v[182:183]
	s_nop 1
	v_mov_b64_e32 v[6:7], v[212:213]
	v_mov_b64_e32 v[8:9], v[214:215]
	v_pk_mul_f32 v[76:77], v[76:77], v[12:13] op_sel_hi:[1,0]
	v_pk_mul_f32 v[78:79], v[78:79], v[12:13] op_sel_hi:[1,0]
	v_pk_mul_f32 v[70:71], v[70:71], v[12:13] op_sel_hi:[1,0]
	v_pk_mul_f32 v[34:35], v[34:35], v[12:13] op_sel_hi:[1,0]
	v_pk_mul_f32 v[38:39], v[38:39], v[12:13] op_sel_hi:[1,0]
	v_pk_mul_f32 v[36:37], v[36:37], v[12:13] op_sel_hi:[1,0]
	v_pk_mul_f32 v[46:47], v[46:47], v[12:13] op_sel_hi:[1,0]
	v_pk_mul_f32 v[40:41], v[40:41], v[12:13] op_sel_hi:[1,0]
	v_pk_mul_f32 v[44:45], v[44:45], v[12:13] op_sel_hi:[1,0]
	v_pk_mul_f32 v[50:51], v[50:51], v[12:13] op_sel_hi:[1,0]
	v_pk_mul_f32 v[48:49], v[48:49], v[12:13] op_sel_hi:[1,0]
	v_pk_mul_f32 v[54:55], v[54:55], v[12:13] op_sel_hi:[1,0]
	v_pk_mul_f32 v[52:53], v[52:53], v[12:13] op_sel_hi:[1,0]
	s_waitcnt vmcnt(0)
	v_pk_fma_f32 v[6:7], v[2:3], v[76:77], v[6:7]
	v_lshl_add_u64 v[2:3], s[34:35], 0, v[86:87]
	v_lshl_add_u64 v[76:77], v[2:3], 0, s[22:23]
	v_add_co_u32_e32 v104, vcc, s8, v76
	v_pk_fma_f32 v[8:9], v[4:5], v[78:79], v[8:9]
	s_nop 0
	v_addc_co_u32_e32 v105, vcc, -1, v77, vcc
	global_store_dwordx4 v[104:105], v[6:9], off offset:-3072
	ds_read_b128 v[2:5], v127
	v_lshl_add_u64 v[86:87], s[18:19], 0, v[86:87]
	ds_read_b128 v[96:99], v127 offset:8192
	s_mov_b32 s8, 0xef2fd000
	s_waitcnt lgkmcnt(0)
	v_pk_add_f32 v[4:5], v[4:5], 1.0 op_sel_hi:[1,0]
	v_pk_add_f32 v[78:79], v[2:3], 1.0 op_sel_hi:[1,0]
	s_nop 0
	v_pk_fma_f32 v[2:3], v[4:5], v[8:9], v[98:99]
	v_pk_fma_f32 v[4:5], v[78:79], v[6:7], v[96:97]
	s_nop 0
	s_nop 0
	s_nop 0
	s_nop 0
	s_nop 0
	s_nop 0
	v_cvt_pk_bf16_f32 v6, v4, v5
	s_nop 0
	s_nop 0
	s_nop 0
	s_nop 0
	v_add_co_u32_e32 v78, vcc, s8, v32
	v_cvt_pk_bf16_f32 v7, v2, v3
	s_nop 0
	v_addc_co_u32_e32 v79, vcc, -1, v33, vcc
	global_store_dwordx2 v[78:79], v[6:7], off offset:-3584
	s_nop 1
	v_mov_b64_e32 v[6:7], v[184:185]
	v_mov_b64_e32 v[8:9], v[186:187]
	s_nop 0
	s_nop 1
	v_mov_b64_e32 v[96:97], v[216:217]
	v_mov_b64_e32 v[98:99], v[218:219]
	v_pk_mul_f32 v[32:33], v[74:75], v[12:13] op_sel_hi:[1,0]
	s_lshl_b64 s[8:9], s[36:37], 13
	s_add_u32 s40, s34, s8
	s_addc_u32 s41, s35, s9
	s_waitcnt vmcnt(0)
	v_pk_fma_f32 v[96:97], v[6:7], v[70:71], v[96:97]
	v_pk_fma_f32 v[98:99], v[8:9], v[32:33], v[98:99]
	global_store_dwordx4 v[104:105], v[96:99], off offset:-2048
	ds_read_b128 v[6:9], v127 offset:1024
	ds_read_b128 v[100:103], v127 offset:9216
	s_waitcnt lgkmcnt(0)
	v_pk_add_f32 v[8:9], v[8:9], 1.0 op_sel_hi:[1,0]
	v_pk_add_f32 v[32:33], v[6:7], 1.0 op_sel_hi:[1,0]
	s_nop 0
	v_pk_fma_f32 v[6:7], v[8:9], v[98:99], v[102:103]
	v_pk_fma_f32 v[8:9], v[32:33], v[96:97], v[100:101]
	s_nop 0
	s_nop 0
	s_nop 0
	s_nop 0
	s_nop 0
	s_nop 0
	v_cvt_pk_bf16_f32 v32, v8, v9
	s_nop 0
	s_nop 0
	s_nop 0
	s_nop 0
	s_nop 0
	v_cvt_pk_bf16_f32 v33, v6, v7
	global_store_dwordx2 v[78:79], v[32:33], off offset:-3072
	s_nop 1
	v_mov_b64_e32 v[96:97], v[188:189]
	v_mov_b64_e32 v[98:99], v[190:191]
	s_nop 1
	v_mov_b64_e32 v[100:101], v[220:221]
	v_mov_b64_e32 v[102:103], v[222:223]
	v_pk_mul_f32 v[32:33], v[72:73], v[12:13] op_sel_hi:[1,0]
	s_waitcnt vmcnt(0)
	v_pk_fma_f32 v[70:71], v[96:97], v[34:35], v[100:101]
	v_pk_fma_f32 v[72:73], v[98:99], v[32:33], v[102:103]
	global_store_dwordx4 v[104:105], v[70:73], off offset:-1024
	ds_read_b128 v[32:35], v127 offset:2048
	ds_read_b128 v[96:99], v127 offset:10240
	s_waitcnt lgkmcnt(0)
	v_pk_add_f32 v[34:35], v[34:35], 1.0 op_sel_hi:[1,0]
	v_pk_add_f32 v[74:75], v[32:33], 1.0 op_sel_hi:[1,0]
	s_nop 0
	v_pk_fma_f32 v[32:33], v[34:35], v[72:73], v[98:99]
	v_pk_fma_f32 v[34:35], v[74:75], v[70:71], v[96:97]
	s_nop 0
	s_nop 0
	s_nop 0
	s_nop 0
	s_nop 0
	s_nop 0
	v_cvt_pk_bf16_f32 v70, v34, v35
	s_nop 0
	s_nop 0
	s_nop 0
	s_nop 0
	s_nop 0
	v_cvt_pk_bf16_f32 v71, v32, v33
	global_store_dwordx2 v[78:79], v[70:71], off offset:-2560
	s_nop 1
	v_mov_b64_e32 v[70:71], v[192:193]
	v_mov_b64_e32 v[72:73], v[194:195]
	s_nop 0
	s_nop 1
	v_mov_b64_e32 v[96:97], v[236:237]
	v_mov_b64_e32 v[98:99], v[238:239]
	s_waitcnt vmcnt(0)
	v_pk_fma_f32 v[70:71], v[70:71], v[36:37], v[96:97]
	v_pk_fma_f32 v[72:73], v[72:73], v[38:39], v[98:99]
	global_store_dwordx4 v[76:77], v[70:73], off offset:-4096
	ds_read_b128 v[36:39], v127 offset:3072
	ds_read_b128 v[96:99], v127 offset:11264
	s_waitcnt lgkmcnt(0)
	v_pk_add_f32 v[38:39], v[38:39], 1.0 op_sel_hi:[1,0]
	v_pk_add_f32 v[74:75], v[36:37], 1.0 op_sel_hi:[1,0]
	s_nop 0
	v_pk_fma_f32 v[36:37], v[38:39], v[72:73], v[98:99]
	v_pk_fma_f32 v[38:39], v[74:75], v[70:71], v[96:97]
	s_nop 0
	s_nop 0
	s_nop 0
	s_nop 0
	s_nop 0
	s_nop 0
	v_cvt_pk_bf16_f32 v70, v38, v39
	s_nop 0
	s_nop 0
	s_nop 0
	s_nop 0
	s_nop 0
	v_cvt_pk_bf16_f32 v71, v36, v37
	global_store_dwordx2 v[78:79], v[70:71], off offset:-2048
	v_add_co_u32_e32 v70, vcc, s82, v84
	s_nop 1
	v_addc_co_u32_e32 v71, vcc, 0, v85, vcc
	v_add_co_u32_e32 v72, vcc, s82, v80
	s_nop 1
	v_mov_b64_e32 v[96:97], v[196:197]
	v_mov_b64_e32 v[98:99], v[198:199]
	s_nop 0
	v_addc_co_u32_e32 v73, vcc, 0, v81, vcc
	s_nop 1
	v_mov_b64_e32 v[100:101], v[240:241]
	v_mov_b64_e32 v[102:103], v[242:243]
	v_add_co_u32_e32 v66, vcc, s82, v88
	s_waitcnt vmcnt(0)
	v_pk_fma_f32 v[96:97], v[40:41], v[96:97], v[100:101]
	v_pk_fma_f32 v[98:99], v[46:47], v[98:99], v[102:103]
	v_addc_co_u32_e32 v67, vcc, 0, v89, vcc
	global_store_dwordx4 v[76:77], v[96:99], off offset:-3072
	v_add_co_u32_e32 v80, vcc, s82, v86
	ds_read_b128 v[40:43], v127 offset:4096
	s_nop 0
	v_addc_co_u32_e32 v81, vcc, 0, v87, vcc
	ds_read_b128 v[84:87], v127 offset:12288
	s_waitcnt lgkmcnt(0)
	v_pk_add_f32 v[42:43], v[42:43], 1.0 op_sel_hi:[1,0]
	v_pk_add_f32 v[46:47], v[40:41], 1.0 op_sel_hi:[1,0]
	s_nop 0
	v_pk_fma_f32 v[40:41], v[98:99], v[42:43], v[86:87]
	v_pk_fma_f32 v[42:43], v[96:97], v[46:47], v[84:85]
	s_nop 0
	s_nop 0
	s_nop 0
	s_nop 0
	s_nop 0
	s_nop 0
	v_cvt_pk_bf16_f32 v46, v42, v43
	s_nop 0
	s_nop 0
	s_nop 0
	s_nop 0
	s_nop 0
	v_cvt_pk_bf16_f32 v47, v40, v41
	global_store_dwordx2 v[78:79], v[46:47], off offset:-1536
	s_nop 1
	v_mov_b64_e32 v[84:85], v[200:201]
	v_mov_b64_e32 v[86:87], v[202:203]
	s_nop 1
	v_mov_b64_e32 v[96:97], v[128:129]
	v_mov_b64_e32 v[98:99], v[130:131]
	v_pk_mul_f32 v[46:47], v[68:69], v[12:13] op_sel_hi:[1,0]
	s_waitcnt vmcnt(0)
	v_pk_fma_f32 v[84:85], v[44:45], v[84:85], v[96:97]
	v_pk_fma_f32 v[86:87], v[46:47], v[86:87], v[98:99]
	global_store_dwordx4 v[76:77], v[84:87], off offset:-2048
	ds_read_b128 v[44:47], v127 offset:5120
	ds_read_b128 v[96:99], v127 offset:13312
	s_waitcnt lgkmcnt(0)
	v_pk_add_f32 v[46:47], v[46:47], 1.0 op_sel_hi:[1,0]
	v_pk_add_f32 v[68:69], v[44:45], 1.0 op_sel_hi:[1,0]
	s_nop 0
	v_pk_fma_f32 v[44:45], v[86:87], v[46:47], v[98:99]
	v_pk_fma_f32 v[46:47], v[84:85], v[68:69], v[96:97]
	s_nop 0
	s_nop 0
	s_nop 0
	s_nop 0
	s_nop 0
	s_nop 0
	v_cvt_pk_bf16_f32 v68, v46, v47
	s_nop 0
	s_nop 0
	s_nop 0
	s_nop 0
	s_nop 0
	v_cvt_pk_bf16_f32 v69, v44, v45
	global_store_dwordx2 v[78:79], v[68:69], off offset:-1024
	s_nop 1
	v_mov_b64_e32 v[84:85], v[204:205]
	v_mov_b64_e32 v[86:87], v[206:207]
	s_nop 1
	v_mov_b64_e32 v[96:97], v[132:133]
	v_mov_b64_e32 v[98:99], v[134:135]
	s_waitcnt vmcnt(0)
	v_pk_fma_f32 v[84:85], v[48:49], v[84:85], v[96:97]
	v_pk_fma_f32 v[86:87], v[50:51], v[86:87], v[98:99]
	global_store_dwordx4 v[76:77], v[84:87], off offset:-1024
	ds_read_b128 v[48:51], v127 offset:6144
	ds_read_b128 v[96:99], v127 offset:14336
	s_waitcnt lgkmcnt(0)
	v_pk_add_f32 v[50:51], v[50:51], 1.0 op_sel_hi:[1,0]
	v_pk_add_f32 v[68:69], v[48:49], 1.0 op_sel_hi:[1,0]
	s_nop 0
	v_pk_fma_f32 v[48:49], v[86:87], v[50:51], v[98:99]
	v_pk_fma_f32 v[50:51], v[84:85], v[68:69], v[96:97]
	s_nop 0
	s_nop 0
	s_nop 0
	s_nop 0
	s_nop 0
	s_nop 0
	v_cvt_pk_bf16_f32 v68, v50, v51
	s_nop 0
	s_nop 0
	s_nop 0
	s_nop 0
	s_nop 0
	v_cvt_pk_bf16_f32 v69, v48, v49
	global_store_dwordx2 v[78:79], v[68:69], off offset:-512
	s_nop 1
	v_mov_b64_e32 v[68:69], v[208:209]
	v_mov_b64_e32 v[70:71], v[210:211]
	s_nop 0
	s_nop 1
	v_mov_b64_e32 v[72:73], v[140:141]
	v_mov_b64_e32 v[74:75], v[142:143]
	s_waitcnt vmcnt(0)
	v_pk_fma_f32 v[68:69], v[52:53], v[68:69], v[72:73]
	v_pk_fma_f32 v[70:71], v[54:55], v[70:71], v[74:75]
	global_store_dwordx4 v[76:77], v[68:71], off
	ds_read_b128 v[52:55], v127 offset:7168
	s_nop 0
	global_load_dwordx4 v[64:67], v[80:81], off offset:3072
	v_and_b32_e32 v77, 0xffff0000, v63
	v_and_b32_e32 v76, 0xffff0000, v61
	v_and_b32_e32 v75, 0xffff0000, v59
	v_and_b32_e32 v74, 0xffff0000, v58
	s_waitcnt vmcnt(0) lgkmcnt(0)
	v_pk_add_f32 v[54:55], v[54:55], 1.0 op_sel_hi:[1,0]
	v_pk_add_f32 v[72:73], v[52:53], 1.0 op_sel_hi:[1,0]
	s_nop 0
	v_pk_fma_f32 v[52:53], v[70:71], v[54:55], v[66:67]
	v_pk_fma_f32 v[54:55], v[68:69], v[72:73], v[64:65]
	v_and_b32_e32 v67, 0xffff0000, v62
	v_cvt_pk_bf16_f32 v64, v54, v55
	v_cvt_pk_bf16_f32 v65, v52, v53
	global_store_dwordx2 v[78:79], v[64:65], off
	v_lshlrev_b32_e32 v64, 16, v60
	v_lshlrev_b32_e32 v65, 16, v62
	v_and_b32_e32 v66, 0xffff0000, v60
	v_lshlrev_b32_e32 v70, 16, v61
	v_lshlrev_b32_e32 v71, 16, v63
	v_pk_add_f32 v[60:61], v[64:65], v[66:67]
	v_pk_add_f32 v[62:63], v[70:71], v[76:77]
	v_lshlrev_b32_e32 v69, 16, v59
	v_lshlrev_b32_e32 v68, 16, v58
	v_pk_add_f32 v[60:61], v[60:61], v[62:63]
	v_pk_add_f32 v[58:59], v[68:69], v[74:75]
	v_add_f32_e32 v12, 0, v60
	v_pk_add_f32 v[58:59], v[58:59], v[58:59] op_sel:[0,1] op_sel_hi:[1,0]
	v_add_f32_e32 v22, v12, v61
	v_mov_b32_e32 v59, v21
	v_pk_add_f32 v[58:59], v[22:23], v[58:59]
	v_pk_add_f32 v[60:61], v[26:27], v[24:25]
	v_and_b32_e32 v73, 0xffff0000, v57
	v_pk_add_f32 v[58:59], v[58:59], v[60:61]
	v_lshlrev_b32_e32 v61, 16, v57
	v_lshlrev_b32_e32 v60, 16, v56
	v_and_b32_e32 v72, 0xffff0000, v56
	v_pk_add_f32 v[56:57], v[60:61], v[72:73]
	v_pk_add_f32 v[58:59], v[58:59], v[58:59] op_sel:[0,1] op_sel_hi:[1,0]
	v_pk_add_f32 v[56:57], v[56:57], v[56:57] op_sel:[0,1] op_sel_hi:[1,0]
	v_add_f32_e32 v14, v16, v17
	v_add_f32_e32 v12, v18, v19
	v_mov_b32_e32 v59, v10
	v_mov_b32_e32 v57, v11
	v_pk_add_f32 v[56:57], v[58:59], v[56:57]
	v_pk_add_f32 v[58:59], v[14:15], v[12:13]
	s_nop 0
	v_pk_add_f32 v[56:57], v[56:57], v[58:59]
	s_nop 0
	v_add_f32_e32 v12, v56, v57
	ds_bpermute_b32 v14, v90, v12
	s_waitcnt lgkmcnt(0)
	v_add_f32_e32 v12, v12, v14
	ds_bpermute_b32 v14, v91, v12
	s_waitcnt lgkmcnt(0)
	v_add_f32_e32 v12, v12, v14
	ds_bpermute_b32 v14, v92, v12
	s_waitcnt lgkmcnt(0)
	v_add_f32_e32 v12, v12, v14
	ds_bpermute_b32 v14, v93, v12
	s_waitcnt lgkmcnt(0)
	v_add_f32_e32 v12, v12, v14
	ds_bpermute_b32 v14, v94, v12
	s_waitcnt lgkmcnt(0)
	v_add_f32_e32 v12, v12, v14
	ds_bpermute_b32 v14, v95, v12
	s_waitcnt lgkmcnt(0)
	v_add_f32_e32 v14, v12, v14
	v_fmac_f32_e32 v66, 0xba000000, v14
	v_fmac_f32_e32 v67, 0xba000000, v14
	v_fmac_f32_e32 v76, 0xba000000, v14
	v_fmac_f32_e32 v64, 0xba000000, v14
	v_fmac_f32_e32 v77, 0xba000000, v14
	v_fmac_f32_e32 v65, 0xba000000, v14
	v_pk_mul_f32 v[58:59], v[66:67], v[66:67]
	v_fmac_f32_e32 v70, 0xba000000, v14
	v_fmac_f32_e32 v71, 0xba000000, v14
	v_mov_b32_e32 v62, v65
	v_mov_b32_e32 v63, v67
	v_mov_b32_e32 v56, v64
	v_pk_fma_f32 v[64:65], v[64:65], v[64:65], v[58:59]
	v_mov_b32_e32 v67, v77
	v_mov_b32_e32 v59, v76
	v_pk_mul_f32 v[76:77], v[76:77], v[76:77]
	v_mov_b32_e32 v57, v66
	v_mov_b32_e32 v66, v71
	v_mov_b32_e32 v58, v70
	v_pk_fma_f32 v[70:71], v[70:71], v[70:71], v[76:77]
	v_fmac_f32_e32 v74, 0xba000000, v14
	v_fmac_f32_e32 v75, 0xba000000, v14
	v_fmac_f32_e32 v69, 0xba000000, v14
	v_pk_add_f32 v[64:65], v[64:65], v[70:71]
	v_fmac_f32_e32 v68, 0xba000000, v14
	v_mov_b32_e32 v70, v69
	v_mov_b32_e32 v71, v75
	v_mov_b32_e32 v69, v74
	v_pk_mul_f32 v[76:77], v[70:71], v[70:71]
	v_pk_mul_f32 v[74:75], v[68:69], v[68:69]
	v_fmac_f32_e32 v28, 0xba000000, v14
	v_pk_mov_b32 v[78:79], v[74:75], v[76:77] op_sel:[1,0]
	v_mov_b32_e32 v75, v77
	v_fmac_f32_e32 v29, 0xba000000, v14
	v_fmac_f32_e32 v30, 0xba000000, v14
	v_mul_f32_e32 v12, v28, v28
	v_pk_add_f32 v[74:75], v[78:79], v[74:75]
	v_fmac_f32_e32 v31, 0xba000000, v14
	v_pk_fma_f32 v[76:77], v[28:29], v[28:29], v[12:13] op_sel_hi:[1,1,0]
	v_mul_f32_e32 v12, v30, v30
	v_pk_add_f32 v[64:65], v[64:65], v[64:65] op_sel_hi:[0,1]
	v_pk_add_f32 v[74:75], v[74:75], v[74:75] op_sel_hi:[0,1]
	v_pk_fma_f32 v[78:79], v[30:31], v[30:31], v[12:13] op_sel_hi:[1,1,0]
	v_fmac_f32_e32 v25, 0xba000000, v14
	v_fmac_f32_e32 v27, 0xba000000, v14
	v_fmac_f32_e32 v21, 0xba000000, v14
	v_fmac_f32_e32 v23, 0xba000000, v14
	v_mul_f32_e32 v76, v23, v23
	v_mul_f32_e32 v78, v21, v21
	v_mul_f32_e32 v74, v27, v27
	v_mul_f32_e32 v64, v25, v25
	v_pk_add_f32 v[76:77], v[76:77], v[78:79]
	v_pk_add_f32 v[64:65], v[74:75], v[64:65]
	v_fmac_f32_e32 v72, 0xba000000, v14
	v_pk_add_f32 v[64:65], v[76:77], v[64:65]
	v_fmac_f32_e32 v73, 0xba000000, v14
	v_fmac_f32_e32 v61, 0xba000000, v14
	v_pk_add_f32 v[74:75], v[64:65], v[64:65] op_sel_hi:[0,1]
	v_fmac_f32_e32 v60, 0xba000000, v14
	v_mov_b32_e32 v64, v61
	v_mov_b32_e32 v65, v73
	v_mov_b32_e32 v61, v72
	v_pk_mul_f32 v[76:77], v[64:65], v[64:65]
	v_pk_mul_f32 v[72:73], v[60:61], v[60:61]
	v_fmac_f32_e32 v16, 0xba000000, v14
	v_pk_mov_b32 v[78:79], v[72:73], v[76:77] op_sel:[1,0]
	v_mov_b32_e32 v73, v77
	v_fmac_f32_e32 v17, 0xba000000, v14
	v_fmac_f32_e32 v18, 0xba000000, v14
	v_mul_f32_e32 v12, v16, v16
	v_pk_add_f32 v[72:73], v[78:79], v[72:73]
	v_fmac_f32_e32 v19, 0xba000000, v14
	v_pk_fma_f32 v[76:77], v[16:17], v[16:17], v[12:13] op_sel_hi:[1,1,0]
	v_mul_f32_e32 v12, v18, v18
	v_pk_add_f32 v[72:73], v[72:73], v[72:73] op_sel_hi:[0,1]
	v_pk_fma_f32 v[78:79], v[18:19], v[18:19], v[12:13] op_sel_hi:[1,1,0]
	v_fmac_f32_e32 v13, 0xba000000, v14
	v_fmac_f32_e32 v15, 0xba000000, v14
	v_fmac_f32_e32 v11, 0xba000000, v14
	v_fmac_f32_e32 v10, 0xba000000, v14
	v_mul_f32_e32 v72, v15, v15
	v_mul_f32_e32 v74, v13, v13
	v_mul_f32_e32 v76, v10, v10
	v_mul_f32_e32 v78, v11, v11
	v_pk_add_f32 v[72:73], v[72:73], v[74:75]
	v_lshlrev_b32_e32 v74, 2, v1
	v_pk_add_f32 v[76:77], v[76:77], v[78:79]
	v_ashrrev_i32_e32 v75, 31, v74
	v_pk_add_f32 v[72:73], v[76:77], v[72:73]
	v_lshlrev_b64 v[76:77], 2, v[74:75]
	v_lshl_add_u64 v[80:81], s[12:13], 0, v[76:77]
	v_lshl_add_u64 v[78:79], s[14:15], 0, v[76:77]
	s_nop 1
	v_mov_b64_e32 v[84:85], v[180:181]
	v_mov_b64_e32 v[86:87], v[182:183]
	s_nop 1
	v_mov_b64_e32 v[96:97], v[212:213]
	v_mov_b64_e32 v[98:99], v[214:215]
	v_add_f32_e32 v12, v72, v73
	ds_bpermute_b32 v14, v90, v12
	s_waitcnt lgkmcnt(0)
	v_add_f32_e32 v12, v12, v14
	ds_bpermute_b32 v14, v91, v12
	s_waitcnt lgkmcnt(0)
	v_add_f32_e32 v12, v12, v14
	ds_bpermute_b32 v14, v92, v12
	s_waitcnt lgkmcnt(0)
	v_add_f32_e32 v12, v12, v14
	ds_bpermute_b32 v14, v93, v12
	s_waitcnt lgkmcnt(0)
	v_add_f32_e32 v12, v12, v14
	ds_bpermute_b32 v14, v94, v12
	s_waitcnt lgkmcnt(0)
	v_add_f32_e32 v12, v12, v14
	ds_bpermute_b32 v14, v95, v12
	s_waitcnt lgkmcnt(0)
	v_add_f32_e32 v12, v12, v14
	v_fmamk_f32 v12, v12, 0x3a000000, v250
	v_cmp_gt_f32_e32 vcc, s96, v12
	v_mul_f32_e32 v14, 0x4f800000, v12
	s_nop 0
	v_cndmask_b32_e32 v12, v12, v14, vcc
	v_sqrt_f32_e32 v14, v12
	s_nop 0
	v_add_u32_e32 v20, -1, v14
	v_fma_f32 v22, -v20, v14, v12
	v_cmp_ge_f32_e64 s[10:11], 0, v22
	v_add_u32_e32 v22, 1, v14
	s_nop 0
	v_cndmask_b32_e64 v20, v14, v20, s[10:11]
	v_fma_f32 v14, -v22, v14, v12
	v_cmp_lt_f32_e64 s[10:11], 0, v14
	s_nop 1
	v_cndmask_b32_e64 v14, v20, v22, s[10:11]
	v_mul_f32_e32 v20, 0x37800000, v14
	v_cndmask_b32_e32 v14, v14, v20, vcc
	v_cmp_class_f32_e32 vcc, v12, v251
	s_nop 1
	v_cndmask_b32_e32 v12, v14, v12, vcc
	v_div_scale_f32 v14, s[8:9], v12, v12, 1.0
	v_rcp_f32_e32 v20, v14
	s_mov_b64 s[8:9], 0x25d1e000
	v_fma_f32 v22, -v14, v20, 1.0
	v_fmac_f32_e32 v20, v22, v20
	v_div_scale_f32 v22, vcc, 1.0, v12, 1.0
	v_mul_f32_e32 v24, v22, v20
	v_fma_f32 v26, -v14, v24, v22
	v_fmac_f32_e32 v24, v26, v20
	v_fma_f32 v14, -v14, v24, v22
	v_div_fmas_f32 v14, v14, v20, v24
	v_div_fixup_f32 v14, v14, v12, 1.0
	v_pk_mul_f32 v[56:57], v[56:57], v[14:15] op_sel_hi:[1,0]
	v_pk_mul_f32 v[58:59], v[58:59], v[14:15] op_sel_hi:[1,0]
	s_waitcnt vmcnt(0)
	v_pk_fma_f32 v[96:97], v[84:85], v[56:57], v[96:97]
	v_lshl_add_u64 v[56:57], s[40:41], 0, v[76:77]
	v_pk_fma_f32 v[98:99], v[86:87], v[58:59], v[98:99]
	v_lshl_add_u64 v[86:87], v[56:57], 0, s[8:9]
	s_mov_b32 s8, 0x25d1f000
	v_add_co_u32_e32 v72, vcc, s8, v56
	v_lshl_add_u64 v[84:85], s[20:21], 0, v[76:77]
	s_nop 0
	v_addc_co_u32_e32 v73, vcc, 0, v57, vcc
	ds_read_b128 v[56:59], v127
	v_lshl_add_u64 v[76:77], s[18:19], 0, v[76:77]
	ds_read_b128 v[100:103], v127 offset:8192
	s_mov_b64 s[8:9], 0xcc1b000
	global_store_dwordx4 v[72:73], v[96:99], off offset:-4096
	v_pk_mul_f32 v[66:67], v[66:67], v[14:15] op_sel_hi:[1,0]
	v_pk_mul_f32 v[62:63], v[62:63], v[14:15] op_sel_hi:[1,0]
	v_pk_mul_f32 v[70:71], v[70:71], v[14:15] op_sel_hi:[1,0]
	v_pk_mul_f32 v[68:69], v[68:69], v[14:15] op_sel_hi:[1,0]
	v_pk_mul_f32 v[30:31], v[30:31], v[14:15] op_sel_hi:[1,0]
	v_pk_mul_f32 v[28:29], v[28:29], v[14:15] op_sel_hi:[1,0]
	v_mov_b32_e32 v24, v27
	v_pk_mul_f32 v[24:25], v[24:25], v[14:15] op_sel_hi:[1,0]
	v_pk_mul_f32 v[64:65], v[64:65], v[14:15] op_sel_hi:[1,0]
	v_pk_mul_f32 v[60:61], v[60:61], v[14:15] op_sel_hi:[1,0]
	v_pk_mul_f32 v[18:19], v[18:19], v[14:15] op_sel_hi:[1,0]
	v_pk_mul_f32 v[16:17], v[16:17], v[14:15] op_sel_hi:[1,0]
	v_pk_mul_f32 v[10:11], v[10:11], v[14:15] op_sel_hi:[1,0]
	s_waitcnt lgkmcnt(0)
	v_pk_add_f32 v[58:59], v[58:59], 1.0 op_sel_hi:[1,0]
	v_pk_add_f32 v[88:89], v[56:57], 1.0 op_sel_hi:[1,0]
	s_nop 0
	v_pk_fma_f32 v[56:57], v[58:59], v[98:99], v[102:103]
	v_pk_fma_f32 v[58:59], v[88:89], v[96:97], v[100:101]
	v_lshl_add_u64 v[96:97], v[74:75], 1, s[16:17]
	s_nop 0
	s_nop 0
	s_nop 0
	s_nop 0
	s_nop 0
	v_cvt_pk_bf16_f32 v88, v58, v59
	s_nop 0
	s_nop 0
	s_nop 0
	s_nop 0
	s_nop 0
	v_lshl_add_u64 v[74:75], v[96:97], 0, s[8:9]
	v_add_co_u32_e32 v96, vcc, s61, v96
	v_cvt_pk_bf16_f32 v89, v56, v57
	s_nop 0
	v_addc_co_u32_e32 v97, vcc, 0, v97, vcc
	global_store_dwordx2 v[96:97], v[88:89], off
	s_nop 1
	v_mov_b64_e32 v[96:97], v[184:185]
	v_mov_b64_e32 v[98:99], v[186:187]
	s_nop 0
	s_nop 1
	v_mov_b64_e32 v[100:101], v[216:217]
	v_mov_b64_e32 v[102:103], v[218:219]
	s_waitcnt vmcnt(0)
	v_pk_fma_f32 v[96:97], v[96:97], v[62:63], v[100:101]
	v_pk_fma_f32 v[98:99], v[98:99], v[66:67], v[102:103]
	global_store_dwordx4 v[86:87], v[96:99], off offset:1024
	ds_read_b128 v[100:103], v127 offset:1024
	ds_read_b128 v[104:107], v127 offset:9216
	s_waitcnt lgkmcnt(0)
	v_pk_add_f32 v[66:67], v[100:101], 1.0 op_sel_hi:[1,0]
	s_nop 0
	v_pk_fma_f32 v[66:67], v[66:67], v[96:97], v[104:105]
	v_pk_add_f32 v[62:63], v[102:103], 1.0 op_sel_hi:[1,0]
	v_pk_fma_f32 v[62:63], v[62:63], v[98:99], v[106:107]
	v_cvt_pk_bf16_f32 v88, v66, v67
	v_cvt_pk_bf16_f32 v89, v62, v63
	global_store_dwordx2 v[74:75], v[88:89], off offset:512
	s_nop 1
	v_mov_b64_e32 v[96:97], v[188:189]
	v_mov_b64_e32 v[98:99], v[190:191]
	s_nop 1
	v_mov_b64_e32 v[100:101], v[220:221]
	v_mov_b64_e32 v[102:103], v[222:223]
	s_waitcnt vmcnt(0)
	v_pk_fma_f32 v[96:97], v[96:97], v[68:69], v[100:101]
	v_pk_fma_f32 v[98:99], v[98:99], v[70:71], v[102:103]
	global_store_dwordx4 v[86:87], v[96:99], off offset:2048
	ds_read_b128 v[68:71], v127 offset:2048
	ds_read_b128 v[100:103], v127 offset:10240
	s_waitcnt lgkmcnt(0)
	v_pk_add_f32 v[70:71], v[70:71], 1.0 op_sel_hi:[1,0]
	v_pk_add_f32 v[88:89], v[68:69], 1.0 op_sel_hi:[1,0]
	s_nop 0
	v_pk_fma_f32 v[68:69], v[70:71], v[98:99], v[102:103]
	v_pk_fma_f32 v[70:71], v[88:89], v[96:97], v[100:101]
	s_nop 0
	s_nop 0
	s_nop 0
	s_nop 0
	s_nop 0
	s_nop 0
	v_cvt_pk_bf16_f32 v88, v70, v71
	s_nop 0
	s_nop 0
	s_nop 0
	s_nop 0
	s_nop 0
	v_cvt_pk_bf16_f32 v89, v68, v69
	global_store_dwordx2 v[74:75], v[88:89], off offset:1024
	s_nop 1
	v_mov_b64_e32 v[96:97], v[192:193]
	v_mov_b64_e32 v[98:99], v[194:195]
	s_nop 1
	v_mov_b64_e32 v[100:101], v[236:237]
	v_mov_b64_e32 v[102:103], v[238:239]
	v_add_co_u32_e32 v80, vcc, s82, v80
	s_waitcnt vmcnt(0)
	v_pk_fma_f32 v[96:97], v[96:97], v[28:29], v[100:101]
	v_pk_fma_f32 v[98:99], v[98:99], v[30:31], v[102:103]
	global_store_dwordx4 v[86:87], v[96:99], off offset:3072
	ds_read_b128 v[28:31], v127 offset:3072
	s_nop 0
	ds_read_b128 v[86:89], v127 offset:11264
	v_addc_co_u32_e32 v81, vcc, 0, v81, vcc
	v_add_co_u32_e32 v78, vcc, s82, v78
	s_waitcnt lgkmcnt(0)
	v_pk_add_f32 v[30:31], v[30:31], 1.0 op_sel_hi:[1,0]
	v_pk_add_f32 v[100:101], v[28:29], 1.0 op_sel_hi:[1,0]
	s_nop 0
	v_pk_fma_f32 v[28:29], v[30:31], v[98:99], v[88:89]
	v_pk_fma_f32 v[30:31], v[100:101], v[96:97], v[86:87]
	v_addc_co_u32_e32 v79, vcc, 0, v79, vcc
	s_nop 0
	s_nop 0
	s_nop 0
	s_nop 0
	s_nop 0
	v_cvt_pk_bf16_f32 v86, v30, v31
	s_nop 0
	s_nop 0
	s_nop 0
	s_nop 0
	s_nop 0
	v_cvt_pk_bf16_f32 v87, v28, v29
	global_store_dwordx2 v[74:75], v[86:87], off offset:1536
	s_nop 1
	v_mov_b64_e32 v[86:87], v[196:197]
	v_mov_b64_e32 v[88:89], v[198:199]
	s_nop 1
	v_mov_b64_e32 v[96:97], v[240:241]
	v_mov_b64_e32 v[98:99], v[242:243]
	v_add_co_u32_e32 v84, vcc, s82, v84
	v_mov_b32_e32 v20, v23
	s_nop 0
	v_addc_co_u32_e32 v85, vcc, 0, v85, vcc
	v_pk_mul_f32 v[20:21], v[20:21], v[14:15] op_sel_hi:[1,0]
	v_add_co_u32_e32 v76, vcc, s82, v76
	s_waitcnt vmcnt(0)
	v_pk_fma_f32 v[22:23], v[20:21], v[86:87], v[96:97]
	v_pk_fma_f32 v[24:25], v[24:25], v[88:89], v[98:99]
	ds_read_b128 v[86:89], v127 offset:4096
	v_addc_co_u32_e32 v77, vcc, 0, v77, vcc
	ds_read_b128 v[96:99], v127 offset:12288
	s_waitcnt lgkmcnt(0)
	v_pk_add_f32 v[26:27], v[86:87], 1.0 op_sel_hi:[1,0]
	global_store_dwordx4 v[72:73], v[22:25], off
	v_pk_add_f32 v[20:21], v[88:89], 1.0 op_sel_hi:[1,0]
	s_nop 0
	v_pk_fma_f32 v[22:23], v[22:23], v[26:27], v[96:97]
	v_pk_fma_f32 v[20:21], v[24:25], v[20:21], v[98:99]
	v_cvt_pk_bf16_f32 v24, v22, v23
	v_cvt_pk_bf16_f32 v25, v20, v21
	global_store_dwordx2 v[74:75], v[24:25], off offset:2048
	s_nop 1
	v_mov_b64_e32 v[24:25], v[200:201]
	v_mov_b64_e32 v[26:27], v[202:203]
	s_nop 0
	s_nop 1
	v_mov_b64_e32 v[86:87], v[128:129]
	v_mov_b64_e32 v[88:89], v[130:131]
	s_waitcnt vmcnt(0)
	v_pk_fma_f32 v[86:87], v[60:61], v[24:25], v[86:87]
	v_pk_fma_f32 v[88:89], v[64:65], v[26:27], v[88:89]
	global_store_dwordx4 v[72:73], v[86:89], off offset:1024
	ds_read_b128 v[24:27], v127 offset:5120
	ds_read_b128 v[96:99], v127 offset:13312
	s_waitcnt lgkmcnt(0)
	v_pk_add_f32 v[26:27], v[26:27], 1.0 op_sel_hi:[1,0]
	v_pk_add_f32 v[60:61], v[24:25], 1.0 op_sel_hi:[1,0]
	s_nop 0
	v_pk_fma_f32 v[24:25], v[88:89], v[26:27], v[98:99]
	v_pk_fma_f32 v[26:27], v[86:87], v[60:61], v[96:97]
	v_cvt_pk_bf16_f32 v60, v26, v27
	v_cvt_pk_bf16_f32 v61, v24, v25
	global_store_dwordx2 v[74:75], v[60:61], off offset:2560
	s_nop 1
	v_mov_b64_e32 v[86:87], v[204:205]
	v_mov_b64_e32 v[88:89], v[206:207]
	s_nop 1
	v_mov_b64_e32 v[96:97], v[132:133]
	v_mov_b64_e32 v[98:99], v[134:135]
	s_waitcnt vmcnt(0)
	v_pk_fma_f32 v[86:87], v[16:17], v[86:87], v[96:97]
	v_pk_fma_f32 v[88:89], v[18:19], v[88:89], v[98:99]
	global_store_dwordx4 v[72:73], v[86:89], off offset:2048
	ds_read_b128 v[16:19], v127 offset:6144
	ds_read_b128 v[96:99], v127 offset:14336
	s_waitcnt lgkmcnt(0)
	v_pk_add_f32 v[18:19], v[18:19], 1.0 op_sel_hi:[1,0]
	v_pk_add_f32 v[60:61], v[16:17], 1.0 op_sel_hi:[1,0]
	s_nop 0
	v_pk_fma_f32 v[16:17], v[88:89], v[18:19], v[98:99]
	v_pk_fma_f32 v[18:19], v[86:87], v[60:61], v[96:97]
	v_cvt_pk_bf16_f32 v60, v18, v19
	v_cvt_pk_bf16_f32 v61, v16, v17
	global_store_dwordx2 v[74:75], v[60:61], off offset:3072
	s_nop 1
	v_mov_b64_e32 v[86:87], v[208:209]
	v_mov_b64_e32 v[88:89], v[210:211]
	s_nop 0
	s_nop 1
	v_mov_b64_e32 v[78:79], v[140:141]
	v_mov_b64_e32 v[80:81], v[142:143]
	v_mov_b32_e32 v12, v15
	v_pk_mul_f32 v[60:61], v[12:13], v[14:15] op_sel_hi:[1,0]
	s_waitcnt vmcnt(0)
	v_pk_fma_f32 v[12:13], v[10:11], v[86:87], v[78:79]
	v_pk_fma_f32 v[14:15], v[60:61], v[88:89], v[80:81]
	global_store_dwordx4 v[72:73], v[12:15], off offset:3072
	ds_read_b128 v[78:81], v127 offset:7168
	s_nop 0
	global_load_dwordx4 v[84:87], v[76:77], off offset:3072
	s_waitcnt vmcnt(0) lgkmcnt(0)
	v_pk_add_f32 v[60:61], v[78:79], 1.0 op_sel_hi:[1,0]
	v_pk_add_f32 v[10:11], v[80:81], 1.0 op_sel_hi:[1,0]
	s_nop 0
	v_pk_fma_f32 v[12:13], v[12:13], v[60:61], v[84:85]
	v_pk_fma_f32 v[10:11], v[14:15], v[10:11], v[86:87]
	v_cvt_pk_bf16_f32 v14, v12, v13
	s_nop 0
	s_nop 0
	s_nop 0
	s_nop 0
	s_nop 0
	v_cvt_pk_bf16_f32 v15, v10, v11
	global_store_dwordx2 v[74:75], v[14:15], off offset:3584
	s_nop 0
	v_lshl_add_u32 v103, v1, 4, 0
	ds_read_b128 v[72:75], v103
	v_add_u32_e32 v80, 0x18400, v103
	s_waitcnt lgkmcnt(0)
	v_pk_fma_f32 v[14:15], v[4:5], v[72:73], 0 op_sel_hi:[1,1,0]
	v_pk_fma_f32 v[60:61], v[58:59], v[72:73], 0 op_sel_hi:[1,1,0]
	v_pk_fma_f32 v[14:15], v[2:3], v[74:75], v[14:15]
	v_pk_fma_f32 v[60:61], v[56:57], v[74:75], v[60:61]
	ds_read_b128 v[72:75], v103 offset:1024
	s_waitcnt lgkmcnt(0)
	v_pk_fma_f32 v[14:15], v[8:9], v[72:73], v[14:15]
	v_pk_fma_f32 v[60:61], v[66:67], v[72:73], v[60:61]
	v_pk_fma_f32 v[14:15], v[6:7], v[74:75], v[14:15]
	v_pk_fma_f32 v[60:61], v[62:63], v[74:75], v[60:61]
	ds_read_b128 v[72:75], v103 offset:2048
	s_waitcnt lgkmcnt(0)
	v_pk_fma_f32 v[14:15], v[34:35], v[72:73], v[14:15]
	v_pk_fma_f32 v[60:61], v[70:71], v[72:73], v[60:61]
	v_pk_fma_f32 v[14:15], v[32:33], v[74:75], v[14:15]
	v_pk_fma_f32 v[60:61], v[68:69], v[74:75], v[60:61]
	ds_read_b128 v[72:75], v103 offset:3072
	s_waitcnt lgkmcnt(0)
	v_pk_fma_f32 v[14:15], v[38:39], v[72:73], v[14:15]
	v_pk_fma_f32 v[60:61], v[30:31], v[72:73], v[60:61]
	v_pk_fma_f32 v[14:15], v[36:37], v[74:75], v[14:15]
	v_pk_fma_f32 v[60:61], v[28:29], v[74:75], v[60:61]
	ds_read_b128 v[72:75], v103 offset:4096
	s_waitcnt lgkmcnt(0)
	v_pk_fma_f32 v[14:15], v[42:43], v[72:73], v[14:15]
	v_pk_fma_f32 v[60:61], v[22:23], v[72:73], v[60:61]
	v_pk_fma_f32 v[14:15], v[40:41], v[74:75], v[14:15]
	v_pk_fma_f32 v[60:61], v[20:21], v[74:75], v[60:61]
	ds_read_b128 v[72:75], v103 offset:5120
	s_waitcnt lgkmcnt(0)
	v_pk_fma_f32 v[14:15], v[46:47], v[72:73], v[14:15]
	v_pk_fma_f32 v[60:61], v[26:27], v[72:73], v[60:61]
	v_pk_fma_f32 v[14:15], v[44:45], v[74:75], v[14:15]
	v_pk_fma_f32 v[60:61], v[24:25], v[74:75], v[60:61]
	ds_read_b128 v[72:75], v103 offset:6144
	s_waitcnt lgkmcnt(0)
	v_pk_fma_f32 v[14:15], v[50:51], v[72:73], v[14:15]
	v_pk_fma_f32 v[60:61], v[18:19], v[72:73], v[60:61]
	v_pk_fma_f32 v[14:15], v[48:49], v[74:75], v[14:15]
	v_pk_fma_f32 v[60:61], v[16:17], v[74:75], v[60:61]
	ds_read_b128 v[72:75], v103 offset:7168
	s_waitcnt lgkmcnt(0)
	v_pk_fma_f32 v[14:15], v[54:55], v[72:73], v[14:15]
	v_pk_fma_f32 v[60:61], v[12:13], v[72:73], v[60:61]
	v_pk_fma_f32 v[14:15], v[52:53], v[74:75], v[14:15]
	v_pk_fma_f32 v[60:61], v[10:11], v[74:75], v[60:61]
	v_add_f32_e32 v81, v14, v15
	v_add_f32_e32 v14, v60, v61
	ds_read_b128 v[72:75], v103 offset:8192
	s_waitcnt lgkmcnt(0)
	v_pk_fma_f32 v[60:61], v[4:5], v[72:73], 0 op_sel_hi:[1,1,0]
	v_pk_fma_f32 v[64:65], v[58:59], v[72:73], 0 op_sel_hi:[1,1,0]
	v_pk_fma_f32 v[60:61], v[2:3], v[74:75], v[60:61]
	v_pk_fma_f32 v[64:65], v[56:57], v[74:75], v[64:65]
	ds_read_b128 v[72:75], v103 offset:9216
	s_waitcnt lgkmcnt(0)
	v_pk_fma_f32 v[60:61], v[8:9], v[72:73], v[60:61]
	v_pk_fma_f32 v[64:65], v[66:67], v[72:73], v[64:65]
	v_pk_fma_f32 v[60:61], v[6:7], v[74:75], v[60:61]
	v_pk_fma_f32 v[64:65], v[62:63], v[74:75], v[64:65]
	ds_read_b128 v[72:75], v103 offset:10240
	s_waitcnt lgkmcnt(0)
	v_pk_fma_f32 v[60:61], v[34:35], v[72:73], v[60:61]
	v_pk_fma_f32 v[64:65], v[70:71], v[72:73], v[64:65]
	v_pk_fma_f32 v[60:61], v[32:33], v[74:75], v[60:61]
	v_pk_fma_f32 v[64:65], v[68:69], v[74:75], v[64:65]
	ds_read_b128 v[72:75], v103 offset:11264
	s_waitcnt lgkmcnt(0)
	v_pk_fma_f32 v[60:61], v[38:39], v[72:73], v[60:61]
	v_pk_fma_f32 v[64:65], v[30:31], v[72:73], v[64:65]
	v_pk_fma_f32 v[60:61], v[36:37], v[74:75], v[60:61]
	v_pk_fma_f32 v[64:65], v[28:29], v[74:75], v[64:65]
	ds_read_b128 v[72:75], v103 offset:12288
	s_waitcnt lgkmcnt(0)
	v_pk_fma_f32 v[60:61], v[42:43], v[72:73], v[60:61]
	v_pk_fma_f32 v[64:65], v[22:23], v[72:73], v[64:65]
	v_pk_fma_f32 v[60:61], v[40:41], v[74:75], v[60:61]
	v_pk_fma_f32 v[64:65], v[20:21], v[74:75], v[64:65]
	ds_read_b128 v[72:75], v103 offset:13312
	s_waitcnt lgkmcnt(0)
	v_pk_fma_f32 v[60:61], v[46:47], v[72:73], v[60:61]
	v_pk_fma_f32 v[64:65], v[26:27], v[72:73], v[64:65]
	v_pk_fma_f32 v[60:61], v[44:45], v[74:75], v[60:61]
	v_pk_fma_f32 v[64:65], v[24:25], v[74:75], v[64:65]
	ds_read_b128 v[72:75], v103 offset:14336
	s_waitcnt lgkmcnt(0)
	v_pk_fma_f32 v[60:61], v[50:51], v[72:73], v[60:61]
	v_pk_fma_f32 v[64:65], v[18:19], v[72:73], v[64:65]
	v_pk_fma_f32 v[60:61], v[48:49], v[74:75], v[60:61]
	v_pk_fma_f32 v[64:65], v[16:17], v[74:75], v[64:65]
	ds_read_b128 v[72:75], v103 offset:15360
	s_waitcnt lgkmcnt(0)
	v_pk_fma_f32 v[60:61], v[54:55], v[72:73], v[60:61]
	v_pk_fma_f32 v[64:65], v[12:13], v[72:73], v[64:65]
	v_pk_fma_f32 v[60:61], v[52:53], v[74:75], v[60:61]
	v_pk_fma_f32 v[64:65], v[10:11], v[74:75], v[64:65]
	v_add_f32_e32 v82, v60, v61
	v_add_f32_e32 v15, v64, v65
	ds_read_b128 v[72:75], v103 offset:16384
	s_waitcnt lgkmcnt(0)
	v_pk_fma_f32 v[60:61], v[4:5], v[72:73], 0 op_sel_hi:[1,1,0]
	v_pk_fma_f32 v[64:65], v[58:59], v[72:73], 0 op_sel_hi:[1,1,0]
	v_pk_fma_f32 v[60:61], v[2:3], v[74:75], v[60:61]
	v_pk_fma_f32 v[64:65], v[56:57], v[74:75], v[64:65]
	ds_read_b128 v[72:75], v103 offset:17408
	s_waitcnt lgkmcnt(0)
	v_pk_fma_f32 v[60:61], v[8:9], v[72:73], v[60:61]
	v_pk_fma_f32 v[64:65], v[66:67], v[72:73], v[64:65]
	v_pk_fma_f32 v[60:61], v[6:7], v[74:75], v[60:61]
	v_pk_fma_f32 v[64:65], v[62:63], v[74:75], v[64:65]
	ds_read_b128 v[72:75], v103 offset:18432
	s_waitcnt lgkmcnt(0)
	v_pk_fma_f32 v[60:61], v[34:35], v[72:73], v[60:61]
	v_pk_fma_f32 v[64:65], v[70:71], v[72:73], v[64:65]
	v_pk_fma_f32 v[60:61], v[32:33], v[74:75], v[60:61]
	v_pk_fma_f32 v[64:65], v[68:69], v[74:75], v[64:65]
	ds_read_b128 v[72:75], v103 offset:19456
	s_waitcnt lgkmcnt(0)
	v_pk_fma_f32 v[60:61], v[38:39], v[72:73], v[60:61]
	v_pk_fma_f32 v[64:65], v[30:31], v[72:73], v[64:65]
	v_pk_fma_f32 v[60:61], v[36:37], v[74:75], v[60:61]
	v_pk_fma_f32 v[64:65], v[28:29], v[74:75], v[64:65]
	ds_read_b128 v[72:75], v103 offset:20480
	s_waitcnt lgkmcnt(0)
	v_pk_fma_f32 v[60:61], v[42:43], v[72:73], v[60:61]
	v_pk_fma_f32 v[64:65], v[22:23], v[72:73], v[64:65]
	v_pk_fma_f32 v[60:61], v[40:41], v[74:75], v[60:61]
	v_pk_fma_f32 v[64:65], v[20:21], v[74:75], v[64:65]
	ds_read_b128 v[72:75], v103 offset:21504
	s_waitcnt lgkmcnt(0)
	v_pk_fma_f32 v[60:61], v[46:47], v[72:73], v[60:61]
	v_pk_fma_f32 v[64:65], v[26:27], v[72:73], v[64:65]
	v_pk_fma_f32 v[60:61], v[44:45], v[74:75], v[60:61]
	v_pk_fma_f32 v[64:65], v[24:25], v[74:75], v[64:65]
	ds_read_b128 v[72:75], v103 offset:22528
	s_waitcnt lgkmcnt(0)
	v_pk_fma_f32 v[60:61], v[50:51], v[72:73], v[60:61]
	v_pk_fma_f32 v[64:65], v[18:19], v[72:73], v[64:65]
	v_pk_fma_f32 v[60:61], v[48:49], v[74:75], v[60:61]
	v_pk_fma_f32 v[64:65], v[16:17], v[74:75], v[64:65]
	ds_read_b128 v[72:75], v103 offset:23552
	s_waitcnt lgkmcnt(0)
	v_pk_fma_f32 v[60:61], v[54:55], v[72:73], v[60:61]
	v_pk_fma_f32 v[64:65], v[12:13], v[72:73], v[64:65]
	v_pk_fma_f32 v[60:61], v[52:53], v[74:75], v[60:61]
	v_pk_fma_f32 v[64:65], v[10:11], v[74:75], v[64:65]
	v_add_f32_e32 v84, v60, v61
	v_add_f32_e32 v60, v64, v65
	ds_read_b128 v[72:75], v103 offset:24576
	s_waitcnt lgkmcnt(0)
	v_pk_fma_f32 v[64:65], v[4:5], v[72:73], 0 op_sel_hi:[1,1,0]
	v_pk_fma_f32 v[72:73], v[58:59], v[72:73], 0 op_sel_hi:[1,1,0]
	v_pk_fma_f32 v[64:65], v[2:3], v[74:75], v[64:65]
	v_pk_fma_f32 v[76:77], v[56:57], v[74:75], v[72:73]
	ds_read_b128 v[72:75], v103 offset:25600
	s_waitcnt lgkmcnt(0)
	v_pk_fma_f32 v[64:65], v[8:9], v[72:73], v[64:65]
	v_pk_fma_f32 v[72:73], v[66:67], v[72:73], v[76:77]
	v_pk_fma_f32 v[64:65], v[6:7], v[74:75], v[64:65]
	v_pk_fma_f32 v[76:77], v[62:63], v[74:75], v[72:73]
	ds_read_b128 v[72:75], v103 offset:26624
	s_waitcnt lgkmcnt(0)
	v_pk_fma_f32 v[64:65], v[34:35], v[72:73], v[64:65]
	v_pk_fma_f32 v[72:73], v[70:71], v[72:73], v[76:77]
	v_pk_fma_f32 v[64:65], v[32:33], v[74:75], v[64:65]
	v_pk_fma_f32 v[76:77], v[68:69], v[74:75], v[72:73]
	ds_read_b128 v[72:75], v103 offset:27648
	s_waitcnt lgkmcnt(0)
	v_pk_fma_f32 v[64:65], v[38:39], v[72:73], v[64:65]
	v_pk_fma_f32 v[72:73], v[30:31], v[72:73], v[76:77]
	v_pk_fma_f32 v[64:65], v[36:37], v[74:75], v[64:65]
	v_pk_fma_f32 v[76:77], v[28:29], v[74:75], v[72:73]
	ds_read_b128 v[72:75], v103 offset:28672
	s_waitcnt lgkmcnt(0)
	v_pk_fma_f32 v[64:65], v[42:43], v[72:73], v[64:65]
	v_pk_fma_f32 v[72:73], v[22:23], v[72:73], v[76:77]
	v_pk_fma_f32 v[64:65], v[40:41], v[74:75], v[64:65]
	v_pk_fma_f32 v[76:77], v[20:21], v[74:75], v[72:73]
	ds_read_b128 v[72:75], v103 offset:29696
	s_waitcnt lgkmcnt(0)
	v_pk_fma_f32 v[64:65], v[46:47], v[72:73], v[64:65]
	v_pk_fma_f32 v[72:73], v[26:27], v[72:73], v[76:77]
	v_pk_fma_f32 v[64:65], v[44:45], v[74:75], v[64:65]
	v_pk_fma_f32 v[76:77], v[24:25], v[74:75], v[72:73]
	ds_read_b128 v[72:75], v103 offset:30720
	s_waitcnt lgkmcnt(0)
	v_pk_fma_f32 v[64:65], v[50:51], v[72:73], v[64:65]
	v_pk_fma_f32 v[72:73], v[18:19], v[72:73], v[76:77]
	v_pk_fma_f32 v[64:65], v[48:49], v[74:75], v[64:65]
	v_pk_fma_f32 v[76:77], v[16:17], v[74:75], v[72:73]
	ds_read_b128 v[72:75], v103 offset:31744
	s_waitcnt lgkmcnt(0)
	v_pk_fma_f32 v[64:65], v[54:55], v[72:73], v[64:65]
	v_pk_fma_f32 v[72:73], v[12:13], v[72:73], v[76:77]
	v_pk_fma_f32 v[64:65], v[52:53], v[74:75], v[64:65]
	v_pk_fma_f32 v[72:73], v[10:11], v[74:75], v[72:73]
	v_add_f32_e32 v85, v64, v65
	v_add_f32_e32 v61, v72, v73
	ds_read_b128 v[72:75], v103 offset:32768
	s_waitcnt lgkmcnt(0)
	v_pk_fma_f32 v[64:65], v[4:5], v[72:73], 0 op_sel_hi:[1,1,0]
	v_pk_fma_f32 v[72:73], v[58:59], v[72:73], 0 op_sel_hi:[1,1,0]
	v_pk_fma_f32 v[64:65], v[2:3], v[74:75], v[64:65]
	v_pk_fma_f32 v[76:77], v[56:57], v[74:75], v[72:73]
	ds_read_b128 v[72:75], v103 offset:33792
	s_waitcnt lgkmcnt(0)
	v_pk_fma_f32 v[64:65], v[8:9], v[72:73], v[64:65]
	v_pk_fma_f32 v[72:73], v[66:67], v[72:73], v[76:77]
	v_pk_fma_f32 v[64:65], v[6:7], v[74:75], v[64:65]
	v_pk_fma_f32 v[76:77], v[62:63], v[74:75], v[72:73]
	ds_read_b128 v[72:75], v103 offset:34816
	s_waitcnt lgkmcnt(0)
	v_pk_fma_f32 v[64:65], v[34:35], v[72:73], v[64:65]
	v_pk_fma_f32 v[72:73], v[70:71], v[72:73], v[76:77]
	v_pk_fma_f32 v[64:65], v[32:33], v[74:75], v[64:65]
	v_pk_fma_f32 v[76:77], v[68:69], v[74:75], v[72:73]
	ds_read_b128 v[72:75], v103 offset:35840
	s_waitcnt lgkmcnt(0)
	v_pk_fma_f32 v[64:65], v[38:39], v[72:73], v[64:65]
	v_pk_fma_f32 v[72:73], v[30:31], v[72:73], v[76:77]
	v_pk_fma_f32 v[64:65], v[36:37], v[74:75], v[64:65]
	v_pk_fma_f32 v[76:77], v[28:29], v[74:75], v[72:73]
	ds_read_b128 v[72:75], v103 offset:36864
	s_waitcnt lgkmcnt(0)
	v_pk_fma_f32 v[64:65], v[42:43], v[72:73], v[64:65]
	v_pk_fma_f32 v[72:73], v[22:23], v[72:73], v[76:77]
	v_pk_fma_f32 v[64:65], v[40:41], v[74:75], v[64:65]
	v_pk_fma_f32 v[76:77], v[20:21], v[74:75], v[72:73]
	ds_read_b128 v[72:75], v103 offset:37888
	s_waitcnt lgkmcnt(0)
	v_pk_fma_f32 v[64:65], v[46:47], v[72:73], v[64:65]
	v_pk_fma_f32 v[72:73], v[26:27], v[72:73], v[76:77]
	v_pk_fma_f32 v[64:65], v[44:45], v[74:75], v[64:65]
	v_pk_fma_f32 v[76:77], v[24:25], v[74:75], v[72:73]
	ds_read_b128 v[72:75], v103 offset:38912
	s_waitcnt lgkmcnt(0)
	v_pk_fma_f32 v[64:65], v[50:51], v[72:73], v[64:65]
	v_pk_fma_f32 v[72:73], v[18:19], v[72:73], v[76:77]
	v_pk_fma_f32 v[64:65], v[48:49], v[74:75], v[64:65]
	v_pk_fma_f32 v[76:77], v[16:17], v[74:75], v[72:73]
	ds_read_b128 v[72:75], v103 offset:39936
	s_waitcnt lgkmcnt(0)
	v_pk_fma_f32 v[64:65], v[54:55], v[72:73], v[64:65]
	v_pk_fma_f32 v[72:73], v[12:13], v[72:73], v[76:77]
	v_pk_fma_f32 v[64:65], v[52:53], v[74:75], v[64:65]
	v_pk_fma_f32 v[72:73], v[10:11], v[74:75], v[72:73]
	v_add_f32_e32 v86, v64, v65
	v_add_f32_e32 v64, v72, v73
	ds_read_b128 v[72:75], v103 offset:40960
	s_waitcnt lgkmcnt(0)
	v_pk_fma_f32 v[76:77], v[4:5], v[72:73], 0 op_sel_hi:[1,1,0]
	v_pk_fma_f32 v[72:73], v[58:59], v[72:73], 0 op_sel_hi:[1,1,0]
	v_pk_fma_f32 v[76:77], v[2:3], v[74:75], v[76:77]
	v_pk_fma_f32 v[78:79], v[56:57], v[74:75], v[72:73]
	ds_read_b128 v[72:75], v103 offset:41984
	s_waitcnt lgkmcnt(0)
	v_pk_fma_f32 v[76:77], v[8:9], v[72:73], v[76:77]
	v_pk_fma_f32 v[72:73], v[66:67], v[72:73], v[78:79]
	v_pk_fma_f32 v[76:77], v[6:7], v[74:75], v[76:77]
	v_pk_fma_f32 v[78:79], v[62:63], v[74:75], v[72:73]
	ds_read_b128 v[72:75], v103 offset:43008
	s_waitcnt lgkmcnt(0)
	v_pk_fma_f32 v[76:77], v[34:35], v[72:73], v[76:77]
	v_pk_fma_f32 v[72:73], v[70:71], v[72:73], v[78:79]
	v_pk_fma_f32 v[76:77], v[32:33], v[74:75], v[76:77]
	v_pk_fma_f32 v[78:79], v[68:69], v[74:75], v[72:73]
	ds_read_b128 v[72:75], v103 offset:44032
	s_waitcnt lgkmcnt(0)
	v_pk_fma_f32 v[76:77], v[38:39], v[72:73], v[76:77]
	v_pk_fma_f32 v[72:73], v[30:31], v[72:73], v[78:79]
	v_pk_fma_f32 v[76:77], v[36:37], v[74:75], v[76:77]
	v_pk_fma_f32 v[78:79], v[28:29], v[74:75], v[72:73]
	ds_read_b128 v[72:75], v103 offset:45056
	s_waitcnt lgkmcnt(0)
	v_pk_fma_f32 v[76:77], v[42:43], v[72:73], v[76:77]
	v_pk_fma_f32 v[72:73], v[22:23], v[72:73], v[78:79]
	v_pk_fma_f32 v[76:77], v[40:41], v[74:75], v[76:77]
	v_pk_fma_f32 v[78:79], v[20:21], v[74:75], v[72:73]
	ds_read_b128 v[72:75], v103 offset:46080
	s_waitcnt lgkmcnt(0)
	v_pk_fma_f32 v[76:77], v[46:47], v[72:73], v[76:77]
	v_pk_fma_f32 v[72:73], v[26:27], v[72:73], v[78:79]
	v_pk_fma_f32 v[76:77], v[44:45], v[74:75], v[76:77]
	v_pk_fma_f32 v[78:79], v[24:25], v[74:75], v[72:73]
	ds_read_b128 v[72:75], v103 offset:47104
	s_waitcnt lgkmcnt(0)
	v_pk_fma_f32 v[76:77], v[50:51], v[72:73], v[76:77]
	v_pk_fma_f32 v[72:73], v[18:19], v[72:73], v[78:79]
	v_pk_fma_f32 v[76:77], v[48:49], v[74:75], v[76:77]
	v_pk_fma_f32 v[78:79], v[16:17], v[74:75], v[72:73]
	ds_read_b128 v[72:75], v103 offset:48128
	s_waitcnt lgkmcnt(0)
	v_pk_fma_f32 v[76:77], v[54:55], v[72:73], v[76:77]
	v_pk_fma_f32 v[72:73], v[12:13], v[72:73], v[78:79]
	v_pk_fma_f32 v[76:77], v[52:53], v[74:75], v[76:77]
	v_pk_fma_f32 v[72:73], v[10:11], v[74:75], v[72:73]
	v_add_f32_e32 v87, v76, v77
	v_add_f32_e32 v65, v72, v73
	ds_read_b128 v[72:75], v103 offset:49152
	s_waitcnt lgkmcnt(0)
	v_pk_fma_f32 v[76:77], v[4:5], v[72:73], 0 op_sel_hi:[1,1,0]
	v_pk_fma_f32 v[72:73], v[58:59], v[72:73], 0 op_sel_hi:[1,1,0]
	v_pk_fma_f32 v[76:77], v[2:3], v[74:75], v[76:77]
	v_pk_fma_f32 v[78:79], v[56:57], v[74:75], v[72:73]
	ds_read_b128 v[72:75], v103 offset:50176
	s_waitcnt lgkmcnt(0)
	v_pk_fma_f32 v[76:77], v[8:9], v[72:73], v[76:77]
	v_pk_fma_f32 v[72:73], v[66:67], v[72:73], v[78:79]
	v_pk_fma_f32 v[76:77], v[6:7], v[74:75], v[76:77]
	v_pk_fma_f32 v[78:79], v[62:63], v[74:75], v[72:73]
	ds_read_b128 v[72:75], v103 offset:51200
	s_waitcnt lgkmcnt(0)
	v_pk_fma_f32 v[76:77], v[34:35], v[72:73], v[76:77]
	v_pk_fma_f32 v[72:73], v[70:71], v[72:73], v[78:79]
	v_pk_fma_f32 v[76:77], v[32:33], v[74:75], v[76:77]
	v_pk_fma_f32 v[78:79], v[68:69], v[74:75], v[72:73]
	ds_read_b128 v[72:75], v103 offset:52224
	s_waitcnt lgkmcnt(0)
	v_pk_fma_f32 v[76:77], v[38:39], v[72:73], v[76:77]
	v_pk_fma_f32 v[72:73], v[30:31], v[72:73], v[78:79]
	v_pk_fma_f32 v[76:77], v[36:37], v[74:75], v[76:77]
	v_pk_fma_f32 v[78:79], v[28:29], v[74:75], v[72:73]
	ds_read_b128 v[72:75], v103 offset:53248
	s_waitcnt lgkmcnt(0)
	v_pk_fma_f32 v[76:77], v[42:43], v[72:73], v[76:77]
	v_pk_fma_f32 v[72:73], v[22:23], v[72:73], v[78:79]
	v_pk_fma_f32 v[76:77], v[40:41], v[74:75], v[76:77]
	v_pk_fma_f32 v[78:79], v[20:21], v[74:75], v[72:73]
	ds_read_b128 v[72:75], v103 offset:54272
	s_waitcnt lgkmcnt(0)
	v_pk_fma_f32 v[76:77], v[46:47], v[72:73], v[76:77]
	v_pk_fma_f32 v[72:73], v[26:27], v[72:73], v[78:79]
	v_pk_fma_f32 v[76:77], v[44:45], v[74:75], v[76:77]
	v_pk_fma_f32 v[78:79], v[24:25], v[74:75], v[72:73]
	ds_read_b128 v[72:75], v103 offset:55296
	s_waitcnt lgkmcnt(0)
	v_pk_fma_f32 v[76:77], v[50:51], v[72:73], v[76:77]
	v_pk_fma_f32 v[72:73], v[18:19], v[72:73], v[78:79]
	v_pk_fma_f32 v[76:77], v[48:49], v[74:75], v[76:77]
	v_pk_fma_f32 v[78:79], v[16:17], v[74:75], v[72:73]
	ds_read_b128 v[72:75], v103 offset:56320
	s_waitcnt lgkmcnt(0)
	v_pk_fma_f32 v[76:77], v[54:55], v[72:73], v[76:77]
	v_pk_fma_f32 v[72:73], v[12:13], v[72:73], v[78:79]
	v_pk_fma_f32 v[76:77], v[52:53], v[74:75], v[76:77]
	v_pk_fma_f32 v[72:73], v[10:11], v[74:75], v[72:73]
	v_add_f32_e32 v88, v76, v77
	v_add_f32_e32 v72, v72, v73
	ds_read_b128 v[74:77], v103 offset:57344
	s_waitcnt lgkmcnt(0)
	v_pk_fma_f32 v[78:79], v[4:5], v[74:75], 0 op_sel_hi:[1,1,0]
	v_pk_fma_f32 v[74:75], v[58:59], v[74:75], 0 op_sel_hi:[1,1,0]
	v_pk_fma_f32 v[78:79], v[2:3], v[76:77], v[78:79]
	v_pk_fma_f32 v[96:97], v[56:57], v[76:77], v[74:75]
	ds_read_b128 v[74:77], v103 offset:58368
	s_waitcnt lgkmcnt(0)
	v_pk_fma_f32 v[78:79], v[8:9], v[74:75], v[78:79]
	v_pk_fma_f32 v[74:75], v[66:67], v[74:75], v[96:97]
	v_pk_fma_f32 v[78:79], v[6:7], v[76:77], v[78:79]
	v_pk_fma_f32 v[96:97], v[62:63], v[76:77], v[74:75]
	ds_read_b128 v[74:77], v103 offset:59392
	s_waitcnt lgkmcnt(0)
	v_pk_fma_f32 v[78:79], v[34:35], v[74:75], v[78:79]
	v_pk_fma_f32 v[74:75], v[70:71], v[74:75], v[96:97]
	v_pk_fma_f32 v[78:79], v[32:33], v[76:77], v[78:79]
	v_pk_fma_f32 v[96:97], v[68:69], v[76:77], v[74:75]
	ds_read_b128 v[74:77], v103 offset:60416
	s_waitcnt lgkmcnt(0)
	v_pk_fma_f32 v[78:79], v[38:39], v[74:75], v[78:79]
	v_pk_fma_f32 v[74:75], v[30:31], v[74:75], v[96:97]
	v_pk_fma_f32 v[78:79], v[36:37], v[76:77], v[78:79]
	v_pk_fma_f32 v[96:97], v[28:29], v[76:77], v[74:75]
	ds_read_b128 v[74:77], v103 offset:61440
	s_waitcnt lgkmcnt(0)
	v_pk_fma_f32 v[78:79], v[42:43], v[74:75], v[78:79]
	v_pk_fma_f32 v[74:75], v[22:23], v[74:75], v[96:97]
	v_pk_fma_f32 v[78:79], v[40:41], v[76:77], v[78:79]
	v_pk_fma_f32 v[96:97], v[20:21], v[76:77], v[74:75]
	ds_read_b128 v[74:77], v103 offset:62464
	s_waitcnt lgkmcnt(0)
	v_pk_fma_f32 v[78:79], v[46:47], v[74:75], v[78:79]
	v_pk_fma_f32 v[74:75], v[26:27], v[74:75], v[96:97]
	v_pk_fma_f32 v[78:79], v[44:45], v[76:77], v[78:79]
	v_pk_fma_f32 v[96:97], v[24:25], v[76:77], v[74:75]
	ds_read_b128 v[74:77], v103 offset:63488
	s_waitcnt lgkmcnt(0)
	v_pk_fma_f32 v[78:79], v[50:51], v[74:75], v[78:79]
	v_pk_fma_f32 v[74:75], v[18:19], v[74:75], v[96:97]
	v_pk_fma_f32 v[78:79], v[48:49], v[76:77], v[78:79]
	v_pk_fma_f32 v[96:97], v[16:17], v[76:77], v[74:75]
	ds_read_b128 v[74:77], v103 offset:64512
	s_waitcnt lgkmcnt(0)
	v_pk_fma_f32 v[78:79], v[54:55], v[74:75], v[78:79]
	v_pk_fma_f32 v[74:75], v[12:13], v[74:75], v[96:97]
	v_pk_fma_f32 v[78:79], v[52:53], v[76:77], v[78:79]
	v_pk_fma_f32 v[74:75], v[10:11], v[76:77], v[74:75]
	v_add_f32_e32 v89, v78, v79
	v_add_f32_e32 v73, v74, v75
	v_add_u32_e32 v74, 0x10000, v103
	ds_read_b128 v[74:77], v74
	s_waitcnt lgkmcnt(0)
	v_pk_fma_f32 v[78:79], v[4:5], v[74:75], 0 op_sel_hi:[1,1,0]
	v_pk_fma_f32 v[74:75], v[58:59], v[74:75], 0 op_sel_hi:[1,1,0]
	v_pk_fma_f32 v[78:79], v[2:3], v[76:77], v[78:79]
	v_pk_fma_f32 v[96:97], v[56:57], v[76:77], v[74:75]
	v_add_u32_e32 v74, 0x10400, v103
	ds_read_b128 v[74:77], v74
	s_waitcnt lgkmcnt(0)
	v_pk_fma_f32 v[78:79], v[8:9], v[74:75], v[78:79]
	v_pk_fma_f32 v[74:75], v[66:67], v[74:75], v[96:97]
	v_pk_fma_f32 v[78:79], v[6:7], v[76:77], v[78:79]
	v_pk_fma_f32 v[96:97], v[62:63], v[76:77], v[74:75]
	v_add_u32_e32 v74, 0x10800, v103
	ds_read_b128 v[74:77], v74
	s_waitcnt lgkmcnt(0)
	v_pk_fma_f32 v[78:79], v[34:35], v[74:75], v[78:79]
	v_pk_fma_f32 v[74:75], v[70:71], v[74:75], v[96:97]
	v_pk_fma_f32 v[78:79], v[32:33], v[76:77], v[78:79]
	v_pk_fma_f32 v[96:97], v[68:69], v[76:77], v[74:75]
	v_add_u32_e32 v74, 0x10c00, v103
	ds_read_b128 v[74:77], v74
	s_waitcnt lgkmcnt(0)
	v_pk_fma_f32 v[78:79], v[38:39], v[74:75], v[78:79]
	v_pk_fma_f32 v[74:75], v[30:31], v[74:75], v[96:97]
	v_pk_fma_f32 v[78:79], v[36:37], v[76:77], v[78:79]
	v_pk_fma_f32 v[96:97], v[28:29], v[76:77], v[74:75]
	v_add_u32_e32 v74, 0x11000, v103
	ds_read_b128 v[74:77], v74
	s_waitcnt lgkmcnt(0)
	v_pk_fma_f32 v[78:79], v[42:43], v[74:75], v[78:79]
	v_pk_fma_f32 v[74:75], v[22:23], v[74:75], v[96:97]
	v_pk_fma_f32 v[78:79], v[40:41], v[76:77], v[78:79]
	v_pk_fma_f32 v[96:97], v[20:21], v[76:77], v[74:75]
	v_add_u32_e32 v74, 0x11400, v103
	ds_read_b128 v[74:77], v74
	s_waitcnt lgkmcnt(0)
	v_pk_fma_f32 v[78:79], v[46:47], v[74:75], v[78:79]
	v_pk_fma_f32 v[74:75], v[26:27], v[74:75], v[96:97]
	v_pk_fma_f32 v[78:79], v[44:45], v[76:77], v[78:79]
	v_pk_fma_f32 v[96:97], v[24:25], v[76:77], v[74:75]
	v_add_u32_e32 v74, 0x11800, v103
	ds_read_b128 v[74:77], v74
	s_waitcnt lgkmcnt(0)
	v_pk_fma_f32 v[78:79], v[50:51], v[74:75], v[78:79]
	v_pk_fma_f32 v[74:75], v[18:19], v[74:75], v[96:97]
	v_pk_fma_f32 v[78:79], v[48:49], v[76:77], v[78:79]
	v_pk_fma_f32 v[96:97], v[16:17], v[76:77], v[74:75]
	v_add_u32_e32 v74, 0x11c00, v103
	ds_read_b128 v[74:77], v74
	s_waitcnt lgkmcnt(0)
	v_pk_fma_f32 v[78:79], v[54:55], v[74:75], v[78:79]
	v_pk_fma_f32 v[74:75], v[12:13], v[74:75], v[96:97]
	v_pk_fma_f32 v[78:79], v[52:53], v[76:77], v[78:79]
	v_pk_fma_f32 v[74:75], v[10:11], v[76:77], v[74:75]
	v_add_f32_e32 v96, v78, v79
	v_add_f32_e32 v74, v74, v75
	v_add_u32_e32 v75, 0x12000, v103
	ds_read_b128 v[76:79], v75
	v_add_u32_e32 v75, 0x12400, v103
	s_waitcnt lgkmcnt(0)
	v_pk_fma_f32 v[98:99], v[4:5], v[76:77], 0 op_sel_hi:[1,1,0]
	v_pk_fma_f32 v[76:77], v[58:59], v[76:77], 0 op_sel_hi:[1,1,0]
	v_pk_fma_f32 v[98:99], v[2:3], v[78:79], v[98:99]
	v_pk_fma_f32 v[100:101], v[56:57], v[78:79], v[76:77]
	ds_read_b128 v[76:79], v75
	v_add_u32_e32 v75, 0x12800, v103
	s_waitcnt lgkmcnt(0)
	v_pk_fma_f32 v[98:99], v[8:9], v[76:77], v[98:99]
	v_pk_fma_f32 v[76:77], v[66:67], v[76:77], v[100:101]
	v_pk_fma_f32 v[98:99], v[6:7], v[78:79], v[98:99]
	v_pk_fma_f32 v[100:101], v[62:63], v[78:79], v[76:77]
	ds_read_b128 v[76:79], v75
	v_add_u32_e32 v75, 0x12c00, v103
	s_waitcnt lgkmcnt(0)
	v_pk_fma_f32 v[98:99], v[34:35], v[76:77], v[98:99]
	v_pk_fma_f32 v[76:77], v[70:71], v[76:77], v[100:101]
	v_pk_fma_f32 v[98:99], v[32:33], v[78:79], v[98:99]
	v_pk_fma_f32 v[100:101], v[68:69], v[78:79], v[76:77]
	ds_read_b128 v[76:79], v75
	v_add_u32_e32 v75, 0x13000, v103
	s_waitcnt lgkmcnt(0)
	v_pk_fma_f32 v[98:99], v[38:39], v[76:77], v[98:99]
	v_pk_fma_f32 v[76:77], v[30:31], v[76:77], v[100:101]
	v_pk_fma_f32 v[98:99], v[36:37], v[78:79], v[98:99]
	v_pk_fma_f32 v[100:101], v[28:29], v[78:79], v[76:77]
	ds_read_b128 v[76:79], v75
	v_add_u32_e32 v75, 0x13400, v103
	s_waitcnt lgkmcnt(0)
	v_pk_fma_f32 v[98:99], v[42:43], v[76:77], v[98:99]
	v_pk_fma_f32 v[76:77], v[22:23], v[76:77], v[100:101]
	v_pk_fma_f32 v[98:99], v[40:41], v[78:79], v[98:99]
	v_pk_fma_f32 v[100:101], v[20:21], v[78:79], v[76:77]
	ds_read_b128 v[76:79], v75
	v_add_u32_e32 v75, 0x13800, v103
	s_waitcnt lgkmcnt(0)
	v_pk_fma_f32 v[98:99], v[46:47], v[76:77], v[98:99]
	v_pk_fma_f32 v[76:77], v[26:27], v[76:77], v[100:101]
	v_pk_fma_f32 v[98:99], v[44:45], v[78:79], v[98:99]
	v_pk_fma_f32 v[100:101], v[24:25], v[78:79], v[76:77]
	ds_read_b128 v[76:79], v75
	v_add_u32_e32 v75, 0x13c00, v103
	s_waitcnt lgkmcnt(0)
	v_pk_fma_f32 v[98:99], v[50:51], v[76:77], v[98:99]
	v_pk_fma_f32 v[76:77], v[18:19], v[76:77], v[100:101]
	v_pk_fma_f32 v[98:99], v[48:49], v[78:79], v[98:99]
	v_pk_fma_f32 v[100:101], v[16:17], v[78:79], v[76:77]
	ds_read_b128 v[76:79], v75
	s_waitcnt lgkmcnt(0)
	v_pk_fma_f32 v[98:99], v[54:55], v[76:77], v[98:99]
	v_pk_fma_f32 v[76:77], v[12:13], v[76:77], v[100:101]
	v_pk_fma_f32 v[98:99], v[52:53], v[78:79], v[98:99]
	v_pk_fma_f32 v[76:77], v[10:11], v[78:79], v[76:77]
	v_add_f32_e32 v97, v98, v99
	v_add_f32_e32 v75, v76, v77
	v_add_u32_e32 v76, 0x14000, v103
	ds_read_b128 v[76:79], v76
	s_waitcnt lgkmcnt(0)
	v_pk_fma_f32 v[98:99], v[4:5], v[76:77], 0 op_sel_hi:[1,1,0]
	v_pk_fma_f32 v[76:77], v[58:59], v[76:77], 0 op_sel_hi:[1,1,0]
	v_pk_fma_f32 v[98:99], v[2:3], v[78:79], v[98:99]
	v_pk_fma_f32 v[100:101], v[56:57], v[78:79], v[76:77]
	v_add_u32_e32 v76, 0x14400, v103
	ds_read_b128 v[76:79], v76
	s_waitcnt lgkmcnt(0)
	v_pk_fma_f32 v[98:99], v[8:9], v[76:77], v[98:99]
	v_pk_fma_f32 v[76:77], v[66:67], v[76:77], v[100:101]
	v_pk_fma_f32 v[98:99], v[6:7], v[78:79], v[98:99]
	v_pk_fma_f32 v[100:101], v[62:63], v[78:79], v[76:77]
	v_add_u32_e32 v76, 0x14800, v103
	ds_read_b128 v[76:79], v76
	s_waitcnt lgkmcnt(0)
	v_pk_fma_f32 v[98:99], v[34:35], v[76:77], v[98:99]
	v_pk_fma_f32 v[76:77], v[70:71], v[76:77], v[100:101]
	v_pk_fma_f32 v[98:99], v[32:33], v[78:79], v[98:99]
	v_pk_fma_f32 v[100:101], v[68:69], v[78:79], v[76:77]
	v_add_u32_e32 v76, 0x14c00, v103
	ds_read_b128 v[76:79], v76
	s_waitcnt lgkmcnt(0)
	v_pk_fma_f32 v[98:99], v[38:39], v[76:77], v[98:99]
	v_pk_fma_f32 v[76:77], v[30:31], v[76:77], v[100:101]
	v_pk_fma_f32 v[98:99], v[36:37], v[78:79], v[98:99]
	v_pk_fma_f32 v[100:101], v[28:29], v[78:79], v[76:77]
	v_add_u32_e32 v76, 0x15000, v103
	ds_read_b128 v[76:79], v76
	s_waitcnt lgkmcnt(0)
	v_pk_fma_f32 v[98:99], v[42:43], v[76:77], v[98:99]
	v_pk_fma_f32 v[76:77], v[22:23], v[76:77], v[100:101]
	v_pk_fma_f32 v[98:99], v[40:41], v[78:79], v[98:99]
	v_pk_fma_f32 v[100:101], v[20:21], v[78:79], v[76:77]
	v_add_u32_e32 v76, 0x15400, v103
	ds_read_b128 v[76:79], v76
	s_waitcnt lgkmcnt(0)
	v_pk_fma_f32 v[98:99], v[46:47], v[76:77], v[98:99]
	v_pk_fma_f32 v[76:77], v[26:27], v[76:77], v[100:101]
	v_pk_fma_f32 v[98:99], v[44:45], v[78:79], v[98:99]
	v_pk_fma_f32 v[100:101], v[24:25], v[78:79], v[76:77]
	v_add_u32_e32 v76, 0x15800, v103
	ds_read_b128 v[76:79], v76
	s_waitcnt lgkmcnt(0)
	v_pk_fma_f32 v[98:99], v[50:51], v[76:77], v[98:99]
	v_pk_fma_f32 v[76:77], v[18:19], v[76:77], v[100:101]
	v_pk_fma_f32 v[98:99], v[48:49], v[78:79], v[98:99]
	v_pk_fma_f32 v[100:101], v[16:17], v[78:79], v[76:77]
	v_add_u32_e32 v76, 0x15c00, v103
	ds_read_b128 v[76:79], v76
	s_waitcnt lgkmcnt(0)
	v_pk_fma_f32 v[98:99], v[54:55], v[76:77], v[98:99]
	v_pk_fma_f32 v[76:77], v[12:13], v[76:77], v[100:101]
	v_pk_fma_f32 v[98:99], v[52:53], v[78:79], v[98:99]
	v_pk_fma_f32 v[76:77], v[10:11], v[78:79], v[76:77]
	v_add_f32_e32 v98, v98, v99
	v_add_f32_e32 v76, v76, v77
	v_add_u32_e32 v77, 0x16000, v103
	ds_read_b128 v[104:107], v77
	v_add_u32_e32 v77, 0x16400, v103
	s_waitcnt lgkmcnt(0)
	v_pk_fma_f32 v[78:79], v[4:5], v[104:105], 0 op_sel_hi:[1,1,0]
	v_pk_fma_f32 v[100:101], v[58:59], v[104:105], 0 op_sel_hi:[1,1,0]
	v_pk_fma_f32 v[78:79], v[2:3], v[106:107], v[78:79]
	v_pk_fma_f32 v[100:101], v[56:57], v[106:107], v[100:101]
	ds_read_b128 v[104:107], v77
	v_add_u32_e32 v77, 0x16800, v103
	s_waitcnt lgkmcnt(0)
	v_pk_fma_f32 v[78:79], v[8:9], v[104:105], v[78:79]
	v_pk_fma_f32 v[100:101], v[66:67], v[104:105], v[100:101]
	v_pk_fma_f32 v[78:79], v[6:7], v[106:107], v[78:79]
	v_pk_fma_f32 v[100:101], v[62:63], v[106:107], v[100:101]
	ds_read_b128 v[104:107], v77
	v_add_u32_e32 v77, 0x16c00, v103
	s_waitcnt lgkmcnt(0)
	v_pk_fma_f32 v[78:79], v[34:35], v[104:105], v[78:79]
	v_pk_fma_f32 v[100:101], v[70:71], v[104:105], v[100:101]
	v_pk_fma_f32 v[78:79], v[32:33], v[106:107], v[78:79]
	v_pk_fma_f32 v[100:101], v[68:69], v[106:107], v[100:101]
	ds_read_b128 v[104:107], v77
	v_add_u32_e32 v77, 0x17000, v103
	s_waitcnt lgkmcnt(0)
	v_pk_fma_f32 v[78:79], v[38:39], v[104:105], v[78:79]
	v_pk_fma_f32 v[100:101], v[30:31], v[104:105], v[100:101]
	v_pk_fma_f32 v[78:79], v[36:37], v[106:107], v[78:79]
	v_pk_fma_f32 v[100:101], v[28:29], v[106:107], v[100:101]
	ds_read_b128 v[104:107], v77
	v_add_u32_e32 v77, 0x17400, v103
	s_waitcnt lgkmcnt(0)
	v_pk_fma_f32 v[78:79], v[42:43], v[104:105], v[78:79]
	v_pk_fma_f32 v[100:101], v[22:23], v[104:105], v[100:101]
	v_pk_fma_f32 v[78:79], v[40:41], v[106:107], v[78:79]
	v_pk_fma_f32 v[100:101], v[20:21], v[106:107], v[100:101]
	ds_read_b128 v[104:107], v77
	v_add_u32_e32 v77, 0x17800, v103
	s_waitcnt lgkmcnt(0)
	v_pk_fma_f32 v[78:79], v[46:47], v[104:105], v[78:79]
	v_pk_fma_f32 v[100:101], v[26:27], v[104:105], v[100:101]
	v_pk_fma_f32 v[78:79], v[44:45], v[106:107], v[78:79]
	v_pk_fma_f32 v[100:101], v[24:25], v[106:107], v[100:101]
	ds_read_b128 v[104:107], v77
	v_add_u32_e32 v77, 0x17c00, v103
	s_waitcnt lgkmcnt(0)
	v_pk_fma_f32 v[78:79], v[50:51], v[104:105], v[78:79]
	v_pk_fma_f32 v[100:101], v[18:19], v[104:105], v[100:101]
	v_pk_fma_f32 v[78:79], v[48:49], v[106:107], v[78:79]
	v_pk_fma_f32 v[100:101], v[16:17], v[106:107], v[100:101]
	ds_read_b128 v[104:107], v77
	s_waitcnt lgkmcnt(0)
	v_pk_fma_f32 v[78:79], v[54:55], v[104:105], v[78:79]
	v_pk_fma_f32 v[100:101], v[12:13], v[104:105], v[100:101]
	v_pk_fma_f32 v[78:79], v[52:53], v[106:107], v[78:79]
	v_pk_fma_f32 v[100:101], v[10:11], v[106:107], v[100:101]
	v_add_f32_e32 v99, v78, v79
	v_add_f32_e32 v77, v100, v101
	v_add_u32_e32 v78, 0x18000, v103
	ds_read_b128 v[104:107], v78
	s_waitcnt lgkmcnt(0)
	v_pk_fma_f32 v[78:79], v[4:5], v[104:105], 0 op_sel_hi:[1,1,0]
	v_pk_fma_f32 v[100:101], v[58:59], v[104:105], 0 op_sel_hi:[1,1,0]
	v_pk_fma_f32 v[78:79], v[2:3], v[106:107], v[78:79]
	v_pk_fma_f32 v[100:101], v[56:57], v[106:107], v[100:101]
	ds_read_b128 v[104:107], v80
	v_add_u32_e32 v80, 0x18800, v103
	s_waitcnt lgkmcnt(0)
	v_pk_fma_f32 v[78:79], v[8:9], v[104:105], v[78:79]
	v_pk_fma_f32 v[100:101], v[66:67], v[104:105], v[100:101]
	v_pk_fma_f32 v[78:79], v[6:7], v[106:107], v[78:79]
	v_pk_fma_f32 v[100:101], v[62:63], v[106:107], v[100:101]
	ds_read_b128 v[104:107], v80
	v_add_u32_e32 v80, 0x18c00, v103
	s_waitcnt lgkmcnt(0)
	v_pk_fma_f32 v[78:79], v[34:35], v[104:105], v[78:79]
	v_pk_fma_f32 v[100:101], v[70:71], v[104:105], v[100:101]
	v_pk_fma_f32 v[78:79], v[32:33], v[106:107], v[78:79]
	v_pk_fma_f32 v[100:101], v[68:69], v[106:107], v[100:101]
	ds_read_b128 v[104:107], v80
	v_add_u32_e32 v80, 0x19000, v103
	s_waitcnt lgkmcnt(0)
	v_pk_fma_f32 v[78:79], v[38:39], v[104:105], v[78:79]
	v_pk_fma_f32 v[100:101], v[30:31], v[104:105], v[100:101]
	v_pk_fma_f32 v[78:79], v[36:37], v[106:107], v[78:79]
	v_pk_fma_f32 v[100:101], v[28:29], v[106:107], v[100:101]
	ds_read_b128 v[104:107], v80
	v_add_u32_e32 v80, 0x19400, v103
	s_waitcnt lgkmcnt(0)
	v_pk_fma_f32 v[78:79], v[42:43], v[104:105], v[78:79]
	v_pk_fma_f32 v[100:101], v[22:23], v[104:105], v[100:101]
	v_pk_fma_f32 v[78:79], v[40:41], v[106:107], v[78:79]
	v_pk_fma_f32 v[100:101], v[20:21], v[106:107], v[100:101]
	ds_read_b128 v[104:107], v80
	v_add_u32_e32 v80, 0x19800, v103
	s_waitcnt lgkmcnt(0)
	v_pk_fma_f32 v[78:79], v[46:47], v[104:105], v[78:79]
	v_pk_fma_f32 v[100:101], v[26:27], v[104:105], v[100:101]
	v_pk_fma_f32 v[78:79], v[44:45], v[106:107], v[78:79]
	v_pk_fma_f32 v[100:101], v[24:25], v[106:107], v[100:101]
	ds_read_b128 v[104:107], v80
	v_add_u32_e32 v80, 0x19c00, v103
	s_waitcnt lgkmcnt(0)
	v_pk_fma_f32 v[78:79], v[50:51], v[104:105], v[78:79]
	v_pk_fma_f32 v[100:101], v[18:19], v[104:105], v[100:101]
	v_pk_fma_f32 v[78:79], v[48:49], v[106:107], v[78:79]
	v_pk_fma_f32 v[100:101], v[16:17], v[106:107], v[100:101]
	ds_read_b128 v[104:107], v80
	v_add_u32_e32 v80, 0x1c000, v103
	s_waitcnt lgkmcnt(0)
	v_pk_fma_f32 v[78:79], v[54:55], v[104:105], v[78:79]
	v_pk_fma_f32 v[100:101], v[12:13], v[104:105], v[100:101]
	v_pk_fma_f32 v[78:79], v[52:53], v[106:107], v[78:79]
	v_pk_fma_f32 v[104:105], v[10:11], v[106:107], v[100:101]
	v_add_f32_e32 v100, v78, v79
	v_add_f32_e32 v78, v104, v105
	v_add_u32_e32 v79, 0x1a000, v103
	ds_read_b128 v[104:107], v79
	v_add_u32_e32 v79, 0x1a400, v103
	s_waitcnt lgkmcnt(0)
	v_pk_fma_f32 v[108:109], v[4:5], v[104:105], 0 op_sel_hi:[1,1,0]
	v_pk_fma_f32 v[104:105], v[58:59], v[104:105], 0 op_sel_hi:[1,1,0]
	v_pk_fma_f32 v[108:109], v[2:3], v[106:107], v[108:109]
	v_pk_fma_f32 v[110:111], v[56:57], v[106:107], v[104:105]
	ds_read_b128 v[104:107], v79
	v_add_u32_e32 v79, 0x1a800, v103
	s_waitcnt lgkmcnt(0)
	v_pk_fma_f32 v[108:109], v[8:9], v[104:105], v[108:109]
	v_pk_fma_f32 v[104:105], v[66:67], v[104:105], v[110:111]
	v_pk_fma_f32 v[108:109], v[6:7], v[106:107], v[108:109]
	v_pk_fma_f32 v[110:111], v[62:63], v[106:107], v[104:105]
	ds_read_b128 v[104:107], v79
	v_add_u32_e32 v79, 0x1ac00, v103
	s_waitcnt lgkmcnt(0)
	v_pk_fma_f32 v[108:109], v[34:35], v[104:105], v[108:109]
	v_pk_fma_f32 v[104:105], v[70:71], v[104:105], v[110:111]
	v_pk_fma_f32 v[108:109], v[32:33], v[106:107], v[108:109]
	v_pk_fma_f32 v[110:111], v[68:69], v[106:107], v[104:105]
	ds_read_b128 v[104:107], v79
	v_add_u32_e32 v79, 0x1b000, v103
	s_waitcnt lgkmcnt(0)
	v_pk_fma_f32 v[108:109], v[38:39], v[104:105], v[108:109]
	v_pk_fma_f32 v[104:105], v[30:31], v[104:105], v[110:111]
	v_pk_fma_f32 v[108:109], v[36:37], v[106:107], v[108:109]
	v_pk_fma_f32 v[110:111], v[28:29], v[106:107], v[104:105]
	ds_read_b128 v[104:107], v79
	v_add_u32_e32 v79, 0x1b400, v103
	s_waitcnt lgkmcnt(0)
	v_pk_fma_f32 v[108:109], v[42:43], v[104:105], v[108:109]
	v_pk_fma_f32 v[104:105], v[22:23], v[104:105], v[110:111]
	v_pk_fma_f32 v[108:109], v[40:41], v[106:107], v[108:109]
	v_pk_fma_f32 v[110:111], v[20:21], v[106:107], v[104:105]
	ds_read_b128 v[104:107], v79
	v_add_u32_e32 v79, 0x1b800, v103
	s_waitcnt lgkmcnt(0)
	v_pk_fma_f32 v[108:109], v[46:47], v[104:105], v[108:109]
	v_pk_fma_f32 v[104:105], v[26:27], v[104:105], v[110:111]
	v_pk_fma_f32 v[108:109], v[44:45], v[106:107], v[108:109]
	v_pk_fma_f32 v[110:111], v[24:25], v[106:107], v[104:105]
	ds_read_b128 v[104:107], v79
	v_add_u32_e32 v79, 0x1bc00, v103
	s_waitcnt lgkmcnt(0)
	v_pk_fma_f32 v[108:109], v[50:51], v[104:105], v[108:109]
	v_pk_fma_f32 v[104:105], v[18:19], v[104:105], v[110:111]
	v_pk_fma_f32 v[108:109], v[48:49], v[106:107], v[108:109]
	v_pk_fma_f32 v[110:111], v[16:17], v[106:107], v[104:105]
	ds_read_b128 v[104:107], v79
	s_waitcnt lgkmcnt(0)
	v_pk_fma_f32 v[108:109], v[54:55], v[104:105], v[108:109]
	v_pk_fma_f32 v[104:105], v[12:13], v[104:105], v[110:111]
	v_pk_fma_f32 v[108:109], v[52:53], v[106:107], v[108:109]
	v_pk_fma_f32 v[104:105], v[10:11], v[106:107], v[104:105]
	v_add_f32_e32 v101, v108, v109
	v_add_f32_e32 v79, v104, v105
	ds_read_b128 v[104:107], v80
	v_add_u32_e32 v80, 0x1c400, v103
	s_waitcnt lgkmcnt(0)
	v_pk_fma_f32 v[108:109], v[4:5], v[104:105], 0 op_sel_hi:[1,1,0]
	v_pk_fma_f32 v[104:105], v[58:59], v[104:105], 0 op_sel_hi:[1,1,0]
	v_pk_fma_f32 v[108:109], v[2:3], v[106:107], v[108:109]
	v_pk_fma_f32 v[110:111], v[56:57], v[106:107], v[104:105]
	ds_read_b128 v[104:107], v80
	v_add_u32_e32 v80, 0x1c800, v103
	s_waitcnt lgkmcnt(0)
	v_pk_fma_f32 v[108:109], v[8:9], v[104:105], v[108:109]
	v_pk_fma_f32 v[104:105], v[66:67], v[104:105], v[110:111]
	v_pk_fma_f32 v[108:109], v[6:7], v[106:107], v[108:109]
	v_pk_fma_f32 v[110:111], v[62:63], v[106:107], v[104:105]
	ds_read_b128 v[104:107], v80
	v_add_u32_e32 v80, 0x1cc00, v103
	s_waitcnt lgkmcnt(0)
	v_pk_fma_f32 v[108:109], v[34:35], v[104:105], v[108:109]
	v_pk_fma_f32 v[104:105], v[70:71], v[104:105], v[110:111]
	v_pk_fma_f32 v[108:109], v[32:33], v[106:107], v[108:109]
	v_pk_fma_f32 v[110:111], v[68:69], v[106:107], v[104:105]
	ds_read_b128 v[104:107], v80
	v_add_u32_e32 v80, 0x1d000, v103
	s_waitcnt lgkmcnt(0)
	v_pk_fma_f32 v[108:109], v[38:39], v[104:105], v[108:109]
	v_pk_fma_f32 v[104:105], v[30:31], v[104:105], v[110:111]
	v_pk_fma_f32 v[108:109], v[36:37], v[106:107], v[108:109]
	v_pk_fma_f32 v[110:111], v[28:29], v[106:107], v[104:105]
	ds_read_b128 v[104:107], v80
	v_add_u32_e32 v80, 0x1d400, v103
	s_waitcnt lgkmcnt(0)
	v_pk_fma_f32 v[108:109], v[42:43], v[104:105], v[108:109]
	v_pk_fma_f32 v[104:105], v[22:23], v[104:105], v[110:111]
	v_pk_fma_f32 v[108:109], v[40:41], v[106:107], v[108:109]
	v_pk_fma_f32 v[110:111], v[20:21], v[106:107], v[104:105]
	ds_read_b128 v[104:107], v80
	v_add_u32_e32 v80, 0x1d800, v103
	s_waitcnt lgkmcnt(0)
	v_pk_fma_f32 v[108:109], v[46:47], v[104:105], v[108:109]
	v_pk_fma_f32 v[104:105], v[26:27], v[104:105], v[110:111]
	v_pk_fma_f32 v[108:109], v[44:45], v[106:107], v[108:109]
	v_pk_fma_f32 v[110:111], v[24:25], v[106:107], v[104:105]
	ds_read_b128 v[104:107], v80
	v_add_u32_e32 v80, 0x1dc00, v103
	s_waitcnt lgkmcnt(0)
	v_pk_fma_f32 v[108:109], v[50:51], v[104:105], v[108:109]
	v_pk_fma_f32 v[104:105], v[18:19], v[104:105], v[110:111]
	v_pk_fma_f32 v[108:109], v[48:49], v[106:107], v[108:109]
	v_pk_fma_f32 v[110:111], v[16:17], v[106:107], v[104:105]
	ds_read_b128 v[104:107], v80
	s_waitcnt lgkmcnt(0)
	v_pk_fma_f32 v[108:109], v[54:55], v[104:105], v[108:109]
	v_pk_fma_f32 v[104:105], v[12:13], v[104:105], v[110:111]
	v_pk_fma_f32 v[108:109], v[52:53], v[106:107], v[108:109]
	v_pk_fma_f32 v[104:105], v[10:11], v[106:107], v[104:105]
	v_add_f32_e32 v102, v108, v109
	v_add_f32_e32 v80, v104, v105
	v_add_u32_e32 v104, 0x1e000, v103
	ds_read_b128 v[104:107], v104
	s_waitcnt lgkmcnt(0)
	v_pk_fma_f32 v[4:5], v[4:5], v[104:105], 0 op_sel_hi:[1,1,0]
	s_nop 0
	v_pk_fma_f32 v[108:109], v[2:3], v[106:107], v[4:5]
	v_pk_fma_f32 v[2:3], v[58:59], v[104:105], 0 op_sel_hi:[1,1,0]
	s_nop 0
	v_pk_fma_f32 v[56:57], v[56:57], v[106:107], v[2:3]
	v_add_u32_e32 v2, 0x1e400, v103
	ds_read_b128 v[2:5], v2
	s_waitcnt lgkmcnt(0)
	v_pk_fma_f32 v[8:9], v[8:9], v[2:3], v[108:109]
	v_pk_fma_f32 v[2:3], v[66:67], v[2:3], v[56:57]
	v_pk_fma_f32 v[6:7], v[6:7], v[4:5], v[8:9]
	v_pk_fma_f32 v[8:9], v[62:63], v[4:5], v[2:3]
	v_add_u32_e32 v2, 0x1e800, v103
	ds_read_b128 v[2:5], v2
	s_waitcnt lgkmcnt(0)
	v_pk_fma_f32 v[6:7], v[34:35], v[2:3], v[6:7]
	v_pk_fma_f32 v[2:3], v[70:71], v[2:3], v[8:9]
	v_pk_fma_f32 v[6:7], v[32:33], v[4:5], v[6:7]
	v_pk_fma_f32 v[8:9], v[68:69], v[4:5], v[2:3]
	v_add_u32_e32 v2, 0x1ec00, v103
	ds_read_b128 v[2:5], v2
	s_waitcnt lgkmcnt(0)
	v_pk_fma_f32 v[6:7], v[38:39], v[2:3], v[6:7]
	v_pk_fma_f32 v[2:3], v[30:31], v[2:3], v[8:9]
	v_pk_fma_f32 v[6:7], v[36:37], v[4:5], v[6:7]
	v_pk_fma_f32 v[8:9], v[28:29], v[4:5], v[2:3]
	v_add_u32_e32 v2, 0x1f000, v103
	ds_read_b128 v[2:5], v2
	s_waitcnt lgkmcnt(0)
	v_pk_fma_f32 v[6:7], v[42:43], v[2:3], v[6:7]
	v_pk_fma_f32 v[2:3], v[22:23], v[2:3], v[8:9]
	v_pk_fma_f32 v[6:7], v[40:41], v[4:5], v[6:7]
	v_pk_fma_f32 v[8:9], v[20:21], v[4:5], v[2:3]
	v_add_u32_e32 v2, 0x1f400, v103
	ds_read_b128 v[2:5], v2
	s_waitcnt lgkmcnt(0)
	v_pk_fma_f32 v[6:7], v[46:47], v[2:3], v[6:7]
	v_pk_fma_f32 v[2:3], v[26:27], v[2:3], v[8:9]
	v_pk_fma_f32 v[6:7], v[44:45], v[4:5], v[6:7]
	v_pk_fma_f32 v[8:9], v[24:25], v[4:5], v[2:3]
	v_add_u32_e32 v2, 0x1f800, v103
	ds_read_b128 v[2:5], v2
	s_waitcnt lgkmcnt(0)
	v_pk_fma_f32 v[6:7], v[50:51], v[2:3], v[6:7]
	v_pk_fma_f32 v[2:3], v[18:19], v[2:3], v[8:9]
	v_pk_fma_f32 v[6:7], v[48:49], v[4:5], v[6:7]
	v_pk_fma_f32 v[8:9], v[16:17], v[4:5], v[2:3]
	v_add_u32_e32 v2, 0x1fc00, v103
	ds_read_b128 v[2:5], v2
	s_waitcnt lgkmcnt(0)
	v_pk_fma_f32 v[6:7], v[54:55], v[2:3], v[6:7]
	v_pk_fma_f32 v[2:3], v[12:13], v[2:3], v[8:9]
	v_pk_fma_f32 v[6:7], v[52:53], v[4:5], v[6:7]
	v_pk_fma_f32 v[4:5], v[10:11], v[4:5], v[2:3]
	v_and_b32_e32 v3, 32, v1
	v_cmp_eq_u32_e32 vcc, 0, v3
	v_add_f32_e32 v4, v4, v5
	v_add_f32_e32 v2, v6, v7
	v_cndmask_b32_e32 v5, v81, v96, vcc
	ds_bpermute_b32 v5, v95, v5
	v_cndmask_b32_e32 v6, v82, v97, vcc
	ds_bpermute_b32 v6, v95, v6
	v_cndmask_b32_e32 v7, v84, v98, vcc
	ds_bpermute_b32 v7, v95, v7
	v_cndmask_b32_e32 v8, v85, v99, vcc
	ds_bpermute_b32 v8, v95, v8
	v_cndmask_b32_e32 v9, v86, v100, vcc
	v_cndmask_b32_e32 v3, v96, v81, vcc
	ds_bpermute_b32 v9, v95, v9
	v_cndmask_b32_e32 v10, v87, v101, vcc
	s_waitcnt lgkmcnt(4)
	v_add_f32_e32 v3, v3, v5
	v_cndmask_b32_e32 v5, v97, v82, vcc
	ds_bpermute_b32 v10, v95, v10
	v_cndmask_b32_e32 v11, v88, v102, vcc
	s_waitcnt lgkmcnt(4)
	v_add_f32_e32 v6, v5, v6
	v_cndmask_b32_e32 v5, v98, v84, vcc
	ds_bpermute_b32 v11, v95, v11
	s_waitcnt lgkmcnt(4)
	v_add_f32_e32 v7, v5, v7
	v_cndmask_b32_e32 v5, v99, v85, vcc
	s_waitcnt lgkmcnt(3)
	v_add_f32_e32 v8, v5, v8
	v_cndmask_b32_e32 v5, v100, v86, vcc
	s_waitcnt lgkmcnt(2)
	v_add_f32_e32 v5, v5, v9
	v_cndmask_b32_e32 v9, v101, v87, vcc
	s_waitcnt lgkmcnt(1)
	v_add_f32_e32 v9, v9, v10
	v_cndmask_b32_e32 v10, v102, v88, vcc
	s_waitcnt lgkmcnt(0)
	v_add_f32_e32 v10, v10, v11
	v_cndmask_b32_e32 v11, v2, v89, vcc
	v_cndmask_b32_e32 v2, v89, v2, vcc
	ds_bpermute_b32 v2, v95, v2
	s_waitcnt lgkmcnt(0)
	v_add_f32_e32 v11, v11, v2
	v_and_b32_e32 v2, 16, v1
	v_cmp_eq_u32_e64 s[10:11], 0, v2
	s_nop 1
	v_cndmask_b32_e64 v2, v5, v3, s[10:11]
	v_cndmask_b32_e64 v3, v3, v5, s[10:11]
	ds_bpermute_b32 v3, v94, v3
	s_waitcnt lgkmcnt(0)
	v_add_f32_e32 v5, v2, v3
	v_cndmask_b32_e64 v3, v6, v9, s[10:11]
	ds_bpermute_b32 v3, v94, v3
	v_cndmask_b32_e64 v2, v9, v6, s[10:11]
	v_cndmask_b32_e64 v6, v7, v10, s[10:11]
	ds_bpermute_b32 v6, v94, v6
	s_waitcnt lgkmcnt(1)
	v_add_f32_e32 v2, v2, v3
	v_cndmask_b32_e64 v3, v10, v7, s[10:11]
	v_cndmask_b32_e64 v7, v8, v11, s[10:11]
	ds_bpermute_b32 v7, v94, v7
	s_waitcnt lgkmcnt(1)
	v_add_f32_e32 v6, v3, v6
	v_cndmask_b32_e64 v3, v11, v8, s[10:11]
	s_waitcnt lgkmcnt(0)
	v_add_f32_e32 v3, v3, v7
	v_and_b32_e32 v7, 8, v1
	v_cmp_eq_u32_e64 s[12:13], 0, v7
	s_nop 1
	v_cndmask_b32_e64 v7, v6, v5, s[12:13]
	v_cndmask_b32_e64 v5, v5, v6, s[12:13]
	v_cndmask_b32_e64 v6, v3, v2, s[12:13]
	v_cndmask_b32_e64 v2, v2, v3, s[12:13]
	ds_bpermute_b32 v5, v93, v5
	ds_bpermute_b32 v2, v93, v2
	v_and_b32_e32 v3, 4, v1
	v_cmp_eq_u32_e64 s[14:15], 0, v3
	s_waitcnt lgkmcnt(1)
	v_add_f32_e32 v5, v7, v5
	s_waitcnt lgkmcnt(0)
	v_add_f32_e32 v2, v6, v2
	v_cndmask_b32_e64 v3, v2, v5, s[14:15]
	v_cndmask_b32_e64 v2, v5, v2, s[14:15]
	ds_bpermute_b32 v2, v92, v2
	v_and_b32_e32 v5, 3, v1
	v_bfe_u32 v1, v1, 2, 4
	v_cmp_eq_u32_e64 s[16:17], 0, v5
	v_lshlrev_b32_e32 v82, 2, v1
	s_waitcnt lgkmcnt(0)
	v_add_f32_e32 v2, v3, v2
	ds_bpermute_b32 v3, v91, v2
	s_waitcnt lgkmcnt(0)
	v_add_f32_e32 v2, v2, v3
	ds_bpermute_b32 v3, v90, v2
	s_and_saveexec_b64 s[40:41], s[16:17]
	s_cbranch_execz .LBB0_1749
	s_waitcnt lgkmcnt(0)
	v_add_f32_e32 v2, v2, v3
	global_load_dword v3, v82, s[38:39] offset:64
	v_cmp_lt_u32_e64 s[18:19], 7, v1
	s_waitcnt vmcnt(0)
	v_add_f32_e32 v5, v2, v3
	s_and_saveexec_b64 s[8:9], s[18:19]
	s_xor_b64 s[54:55], exec, s[8:9]
	s_cbranch_execz .LBB0_1746
	s_mov_b32 s18, 0xbfb8aa3b
	v_mul_f32_e64 v2, |v5|, s18
	v_exp_f32_e32 v6, v2
	s_lshl_b64 s[8:9], s[30:31], 5
	s_add_u32 s8, s58, s8
	s_addc_u32 s9, s59, s9
	v_lshl_add_u64 v[2:3], s[8:9], 0, v[82:83]
	v_add_f32_e32 v6, 1.0, v6
	s_mov_b32 s8, 0x800000
	v_cmp_gt_f32_e64 s[18:19], s8, v6
	s_movk_i32 s8, 0xffe0
	s_mov_b32 s9, -1
	v_cndmask_b32_e64 v7, 0, 32, s[18:19]
	v_ldexp_f32 v6, v6, v7
	v_log_f32_e32 v6, v6
	v_lshl_add_u64 v[2:3], v[2:3], 0, s[8:9]
	s_mov_b32 s8, 0x3f317217
	v_max_f32_e32 v5, v5, v5
	v_mul_f32_e32 v7, 0x3f317217, v6
	v_fma_f32 v7, v6, s8, -v7
	v_fmac_f32_e32 v7, 0x3377d1cf, v6
	s_mov_b32 s8, 0x7f800000
	v_fmac_f32_e32 v7, 0x3f317217, v6
	v_cmp_lt_f32_e64 s[20:21], |v6|, s8
	v_min_f32_e32 v5, 0, v5
	s_nop 0
	v_cndmask_b32_e64 v6, v6, v7, s[20:21]
	v_mov_b32_e32 v7, 0x41b17218
	v_cndmask_b32_e64 v7, 0, v7, s[18:19]
	v_sub_f32_e32 v6, v6, v7
	v_sub_f32_e32 v5, v5, v6
